# FFN1/FFN2 gate-up and in-proj GEMM phases: unaligned epilogues (no extra per-unit barriers; one half's epilogue overlaps the other half's MFMA phase), one compensating barrier at phase exit
# baseline (speedup 1.0000x reference)
; __device__ __forceinline__ unsigned cvt_pk_bf16(float lo, float hi) { f32x2 v = {lo, hi}; bf16x2_t b = __builtin_convertvector(v, bf16x2_t); return __builtin_bit_cast(unsigned, b); }
; __device__ __forceinline__ float fast_exp2(float x) { return __builtin_amdgcn_exp2f(x); }
; __device__ __forceinline__ float fast_rcp(float x) { return __builtin_amdgcn_rcpf(x); }
;     __device__ __forceinline__ void operator()(ACC_T, const Unit& u, int wr, int wc, int fr, int fq) const {
;         const int row0 = wr * 64 + fr, col0 = u.pn * HALF + wc * 32 + 8 * fq; bf16_t* Hp = H + (size_t)u.pm * (SLOTB / 2);
; #pragma unroll
;         for (int ai = 0; ai < 2; ++ai)
; #pragma unroll
;             for (int m = 0; m < 4; ++m) { bf16_t* rowp = Hp + (size_t)(row0 + ai * HALF + m * 16) * DFF + col0; float r[8];
; #pragma unroll
;                 for (int n = 0; n < 2; ++n)
; #pragma unroll
;                     for (int e = 0; e < 4; ++e) { const float g = acc[ai][0][m][n][e], up = acc[ai][1][m][n][e]; r[n * 4 + e] = g * fast_rcp(1.f + fast_exp2(-g * LOG2E)) * up; }
;                 u32x4 w; w.x = cvt_pk_bf16(r[0], r[1]); w.y = cvt_pk_bf16(r[2], r[3]); w.z = cvt_pk_bf16(r[4], r[5]); w.w = cvt_pk_bf16(r[6], r[7]);
;                 *(u32x4*)rowp = w; }
.LBB0_125:
	v_mul_f32_e32 v157, 0xbfb8aa3b, v126
	v_exp_f32_e32 v157, v157
	v_mul_f32_e32 v161, 0xbfb8aa3b, v127
	v_exp_f32_e32 v161, v161
	v_lshl_or_b32 v156, s2, 7, v159
	v_add_f32_e32 v157, 1.0, v157
	v_rcp_f32_e32 v162, v157
	v_add_f32_e32 v157, 1.0, v161
	v_rcp_f32_e32 v163, v157
	v_mul_f32_e32 v161, 0xbfb8aa3b, v128
	v_exp_f32_e32 v161, v161
	s_mul_i32 s2, s3, 0x1c0000
	v_pk_mul_f32 v[126:127], v[126:127], v[162:163]
	v_mul_f32_e32 v162, 0xbfb8aa3b, v129
	v_exp_f32_e32 v162, v162
	v_pk_mul_f32 v[118:119], v[126:127], v[118:119]
	v_add_f32_e32 v126, 1.0, v161
	v_mul_f32_e32 v161, 0xbfb8aa3b, v122
	v_add_f32_e32 v127, 1.0, v162
	v_rcp_f32_e32 v126, v126
	v_rcp_f32_e32 v127, v127
	v_exp_f32_e32 v161, v161
	v_mul_f32_e32 v162, 0xbfb8aa3b, v123
	v_exp_f32_e32 v162, v162
	v_pk_mul_f32 v[126:127], v[128:129], v[126:127]
	v_add_f32_e32 v128, 1.0, v161
	v_mul_f32_e32 v161, 0xbfb8aa3b, v124
	v_add_f32_e32 v129, 1.0, v162
	v_exp_f32_e32 v161, v161
	v_mul_f32_e32 v162, 0xbfb8aa3b, v125
	v_exp_f32_e32 v163, v162
	v_rcp_f32_e32 v128, v128
	v_add_f32_e32 v161, 1.0, v161
	v_rcp_f32_e32 v129, v129
	v_rcp_f32_e32 v162, v161
	v_add_f32_e32 v161, 1.0, v163
	v_rcp_f32_e32 v163, v161
	v_pk_mul_f32 v[122:123], v[122:123], v[128:129]
	v_readlane_b32 s14, v251, 56
	v_pk_mul_f32 v[122:123], v[122:123], v[114:115]
	v_pk_mul_f32 v[114:115], v[124:125], v[162:163]
	s_mul_hi_i32 s7, s3, 0x1c0000
	v_pk_mul_f32 v[124:125], v[114:115], v[116:117]
	v_mul_f32_e32 v115, 0xbfb8aa3b, v110
	v_exp_f32_e32 v116, v115
	v_mul_f32_e32 v115, 0xbfb8aa3b, v111
	v_exp_f32_e32 v117, v115
	v_readlane_b32 s15, v251, 57
	s_add_u32 s2, s14, s2
	s_addc_u32 s3, s15, s7
	v_ashrrev_i32_e32 v157, 31, v156
	v_add_f32_e32 v116, 1.0, v116
	v_lshl_add_u64 v[156:157], v[156:157], 1, s[2:3]
	v_pk_mul_f32 v[120:121], v[126:127], v[120:121]
	v_cvt_pk_bf16_f32 v114, v118, v119
	v_rcp_f32_e32 v118, v116
	v_add_f32_e32 v116, 1.0, v117
	v_lshl_add_u64 v[126:127], v[156:157], 0, v[136:137]
	v_cvt_pk_bf16_f32 v115, v120, v121
	v_rcp_f32_e32 v119, v116
	v_cvt_pk_bf16_f32 v116, v122, v123
	v_cvt_pk_bf16_f32 v117, v124, v125
	global_store_dwordx4 v[126:127], v[114:117], off
	v_pk_mul_f32 v[110:111], v[110:111], v[118:119]
	s_andn2_b64 vcc, exec, s[36:37]
	v_mul_f32_e32 v114, 0xbfb8aa3b, v112
	v_mul_f32_e32 v115, 0xbfb8aa3b, v113
	v_exp_f32_e32 v114, v114
	v_exp_f32_e32 v115, v115
	v_pk_mul_f32 v[102:103], v[110:111], v[102:103]
	s_mov_b64 s[14:15], -1
	v_add_f32_e32 v110, 1.0, v114
	v_add_f32_e32 v111, 1.0, v115
	v_mul_f32_e32 v114, 0xbfb8aa3b, v106
	v_mul_f32_e32 v115, 0xbfb8aa3b, v107
	v_rcp_f32_e32 v110, v110
	v_rcp_f32_e32 v111, v111
	v_exp_f32_e32 v114, v114
	v_exp_f32_e32 v115, v115
	v_pk_mul_f32 v[110:111], v[112:113], v[110:111]
	v_add_f32_e32 v112, 1.0, v114
	v_add_f32_e32 v113, 1.0, v115
	v_mul_f32_e32 v114, 0xbfb8aa3b, v108
	v_mul_f32_e32 v115, 0xbfb8aa3b, v109
	v_exp_f32_e32 v114, v114
	v_exp_f32_e32 v115, v115
	v_rcp_f32_e32 v112, v112
	v_rcp_f32_e32 v113, v113
	v_add_f32_e32 v114, 1.0, v114
	v_add_f32_e32 v115, 1.0, v115
	v_rcp_f32_e32 v114, v114
	v_rcp_f32_e32 v115, v115
	v_pk_mul_f32 v[106:107], v[106:107], v[112:113]
	v_pk_mul_f32 v[104:105], v[110:111], v[104:105]
	v_pk_mul_f32 v[106:107], v[106:107], v[98:99]
	v_pk_mul_f32 v[98:99], v[108:109], v[114:115]
	v_lshl_add_u64 v[110:111], v[156:157], 0, v[138:139]
	v_pk_mul_f32 v[108:109], v[98:99], v[100:101]
	v_mul_f32_e32 v99, 0xbfb8aa3b, v94
	v_exp_f32_e32 v100, v99
	v_mul_f32_e32 v99, 0xbfb8aa3b, v95
	v_exp_f32_e32 v101, v99
	v_cvt_pk_bf16_f32 v98, v102, v103
	v_add_f32_e32 v100, 1.0, v100
	v_rcp_f32_e32 v102, v100
	v_add_f32_e32 v100, 1.0, v101
	v_cvt_pk_bf16_f32 v99, v104, v105
	v_rcp_f32_e32 v103, v100
	v_cvt_pk_bf16_f32 v100, v106, v107
	v_cvt_pk_bf16_f32 v101, v108, v109
	global_store_dwordx4 v[110:111], v[98:101], off
	v_pk_mul_f32 v[94:95], v[94:95], v[102:103]
	s_nop 0
	v_mul_f32_e32 v98, 0xbfb8aa3b, v96
	v_mul_f32_e32 v99, 0xbfb8aa3b, v97
	v_exp_f32_e32 v98, v98
	v_exp_f32_e32 v99, v99
	v_pk_mul_f32 v[86:87], v[94:95], v[86:87]
	v_add_f32_e32 v94, 1.0, v98
	v_add_f32_e32 v95, 1.0, v99
	v_mul_f32_e32 v98, 0xbfb8aa3b, v90
	v_mul_f32_e32 v99, 0xbfb8aa3b, v91
	v_rcp_f32_e32 v94, v94
	v_rcp_f32_e32 v95, v95
	v_exp_f32_e32 v98, v98
	v_exp_f32_e32 v99, v99
	v_pk_mul_f32 v[94:95], v[96:97], v[94:95]
	v_add_f32_e32 v96, 1.0, v98
	v_add_f32_e32 v97, 1.0, v99
	v_mul_f32_e32 v98, 0xbfb8aa3b, v92
	v_mul_f32_e32 v99, 0xbfb8aa3b, v93
	v_exp_f32_e32 v98, v98
	v_exp_f32_e32 v99, v99
	v_rcp_f32_e32 v96, v96
	v_rcp_f32_e32 v97, v97
	v_add_f32_e32 v98, 1.0, v98
	v_add_f32_e32 v99, 1.0, v99
	v_rcp_f32_e32 v98, v98
	v_rcp_f32_e32 v99, v99
	v_pk_mul_f32 v[90:91], v[90:91], v[96:97]
	v_pk_mul_f32 v[88:89], v[94:95], v[88:89]
	v_pk_mul_f32 v[90:91], v[90:91], v[82:83]
	v_pk_mul_f32 v[82:83], v[92:93], v[98:99]
	v_lshl_add_u64 v[94:95], v[156:157], 0, v[140:141]
	v_pk_mul_f32 v[92:93], v[82:83], v[84:85]
	v_mul_f32_e32 v83, 0xbfb8aa3b, v78
	v_exp_f32_e32 v84, v83
	v_mul_f32_e32 v83, 0xbfb8aa3b, v79
	v_exp_f32_e32 v85, v83
	v_cvt_pk_bf16_f32 v82, v86, v87
	v_add_f32_e32 v84, 1.0, v84
	v_rcp_f32_e32 v86, v84
	v_add_f32_e32 v84, 1.0, v85
	v_cvt_pk_bf16_f32 v83, v88, v89
	v_rcp_f32_e32 v87, v84
	v_cvt_pk_bf16_f32 v84, v90, v91
	v_cvt_pk_bf16_f32 v85, v92, v93
	global_store_dwordx4 v[94:95], v[82:85], off
	v_pk_mul_f32 v[78:79], v[78:79], v[86:87]
	s_nop 0
	v_mul_f32_e32 v82, 0xbfb8aa3b, v80
	v_mul_f32_e32 v83, 0xbfb8aa3b, v81
	v_exp_f32_e32 v82, v82
	v_exp_f32_e32 v83, v83
	v_pk_mul_f32 v[70:71], v[78:79], v[70:71]
	v_add_f32_e32 v78, 1.0, v82
	v_add_f32_e32 v79, 1.0, v83
	v_mul_f32_e32 v82, 0xbfb8aa3b, v74
	v_mul_f32_e32 v83, 0xbfb8aa3b, v75
; __device__ __forceinline__ unsigned cvt_pk_bf16(float lo, float hi) { f32x2 v = {lo, hi}; bf16x2_t b = __builtin_convertvector(v, bf16x2_t); return __builtin_bit_cast(unsigned, b); }
; __device__ __forceinline__ float fast_exp2(float x) { return __builtin_amdgcn_exp2f(x); }
; __device__ __forceinline__ float fast_rcp(float x) { return __builtin_amdgcn_rcpf(x); }
; #define PG8_WAIT_V(n) asm volatile("s_waitcnt vmcnt(" #n ")" ::: "memory")
; #define PG8_BAR __builtin_amdgcn_s_barrier()
;     __device__ __forceinline__ void operator()(ACC_T, const Unit& u, int wr, int wc, int fr, int fq) const {
;     ...
;             for (int m = 0; m < 4; ++m) { bf16_t* rowp = Hp + (size_t)(row0 + ai * HALF + m * 16) * DFF + col0; float r[8];
; #pragma unroll
;                 for (int n = 0; n < 2; ++n)
; #pragma unroll
;                     for (int e = 0; e < 4; ++e) { const float g = acc[ai][0][m][n][e], up = acc[ai][1][m][n][e]; r[n * 4 + e] = g * fast_rcp(1.f + fast_exp2(-g * LOG2E)) * up; }
;                 u32x4 w; w.x = cvt_pk_bf16(r[0], r[1]); w.y = cvt_pk_bf16(r[2], r[3]); w.z = cvt_pk_bf16(r[4], r[5]); w.w = cvt_pk_bf16(r[6], r[7]);
;                 *(u32x4*)rowp = w; }
; template <class Epi, bool ALIGN_EPI, bool ASLOT = false>
; __device__ __forceinline__ void gemm_phase(LAS unsigned char* lds, const Gemm g, const Sched& S, const Epi& E) {
;     ...
;         if (!has_next) break;
; #pragma unroll
;         for (int a = 0; a < 2; ++a)
; #pragma unroll
;             for (int b = 0; b < 2; ++b)
; #pragma unroll
;                 for (int m = 0; m < 4; ++m)
; #pragma unroll
;                     for (int n = 0; n < 2; ++n) acc[a][b][m][n] = (f32x4){0.f, 0.f, 0.f, 0.f};
;         cur = nxt; cA = nA; cB = nB; ++ui;
;         if constexpr (ALIGN_EPI) { if (wr == 1) PG8_BAR; }
;     }
;     PG8_WAIT_V(0);
;     if constexpr (!ALIGN_EPI) { if (wr == 0) PG8_BAR; }
	v_rcp_f32_e32 v78, v78
	v_rcp_f32_e32 v79, v79
	v_exp_f32_e32 v82, v82
	v_exp_f32_e32 v83, v83
	v_pk_mul_f32 v[78:79], v[80:81], v[78:79]
	v_add_f32_e32 v80, 1.0, v82
	v_add_f32_e32 v81, 1.0, v83
	v_mul_f32_e32 v82, 0xbfb8aa3b, v76
	v_mul_f32_e32 v83, 0xbfb8aa3b, v77
	v_exp_f32_e32 v82, v82
	v_exp_f32_e32 v83, v83
	v_rcp_f32_e32 v80, v80
	v_rcp_f32_e32 v81, v81
	v_add_f32_e32 v82, 1.0, v82
	v_add_f32_e32 v83, 1.0, v83
	v_rcp_f32_e32 v82, v82
	v_rcp_f32_e32 v83, v83
	v_pk_mul_f32 v[74:75], v[74:75], v[80:81]
	v_pk_mul_f32 v[72:73], v[78:79], v[72:73]
	v_pk_mul_f32 v[74:75], v[74:75], v[66:67]
	v_pk_mul_f32 v[66:67], v[76:77], v[82:83]
	v_lshl_add_u64 v[78:79], v[156:157], 0, v[142:143]
	v_pk_mul_f32 v[76:77], v[66:67], v[68:69]
	v_mul_f32_e32 v67, 0xbfb8aa3b, v62
	v_exp_f32_e32 v68, v67
	v_mul_f32_e32 v67, 0xbfb8aa3b, v63
	v_exp_f32_e32 v69, v67
	v_cvt_pk_bf16_f32 v66, v70, v71
	v_add_f32_e32 v68, 1.0, v68
	v_rcp_f32_e32 v70, v68
	v_add_f32_e32 v68, 1.0, v69
	v_cvt_pk_bf16_f32 v67, v72, v73
	v_rcp_f32_e32 v71, v68
	v_cvt_pk_bf16_f32 v68, v74, v75
	v_cvt_pk_bf16_f32 v69, v76, v77
	global_store_dwordx4 v[78:79], v[66:69], off
	v_pk_mul_f32 v[62:63], v[62:63], v[70:71]
	s_nop 0
	v_mul_f32_e32 v66, 0xbfb8aa3b, v64
	v_mul_f32_e32 v67, 0xbfb8aa3b, v65
	v_exp_f32_e32 v66, v66
	v_exp_f32_e32 v67, v67
	v_pk_mul_f32 v[54:55], v[62:63], v[54:55]
	v_add_f32_e32 v62, 1.0, v66
	v_add_f32_e32 v63, 1.0, v67
	v_mul_f32_e32 v66, 0xbfb8aa3b, v58
	v_mul_f32_e32 v67, 0xbfb8aa3b, v59
	v_rcp_f32_e32 v62, v62
	v_rcp_f32_e32 v63, v63
	v_exp_f32_e32 v66, v66
	v_exp_f32_e32 v67, v67
	v_pk_mul_f32 v[62:63], v[64:65], v[62:63]
	v_add_f32_e32 v64, 1.0, v66
	v_add_f32_e32 v65, 1.0, v67
	v_mul_f32_e32 v66, 0xbfb8aa3b, v60
	v_mul_f32_e32 v67, 0xbfb8aa3b, v61
	v_exp_f32_e32 v66, v66
	v_exp_f32_e32 v67, v67
	v_rcp_f32_e32 v64, v64
	v_rcp_f32_e32 v65, v65
	v_add_f32_e32 v66, 1.0, v66
	v_add_f32_e32 v67, 1.0, v67
	v_rcp_f32_e32 v66, v66
	v_rcp_f32_e32 v67, v67
	v_pk_mul_f32 v[58:59], v[58:59], v[64:65]
	v_pk_mul_f32 v[56:57], v[62:63], v[56:57]
	v_pk_mul_f32 v[58:59], v[58:59], v[50:51]
	v_pk_mul_f32 v[50:51], v[60:61], v[66:67]
	v_lshl_add_u64 v[62:63], v[156:157], 0, v[144:145]
	v_pk_mul_f32 v[60:61], v[50:51], v[52:53]
	v_mul_f32_e32 v51, 0xbfb8aa3b, v46
	v_exp_f32_e32 v52, v51
	v_mul_f32_e32 v51, 0xbfb8aa3b, v47
	v_exp_f32_e32 v53, v51
	v_cvt_pk_bf16_f32 v50, v54, v55
	v_add_f32_e32 v52, 1.0, v52
	v_rcp_f32_e32 v54, v52
	v_add_f32_e32 v52, 1.0, v53
	v_cvt_pk_bf16_f32 v51, v56, v57
	v_rcp_f32_e32 v55, v52
	v_cvt_pk_bf16_f32 v52, v58, v59
	v_cvt_pk_bf16_f32 v53, v60, v61
	global_store_dwordx4 v[62:63], v[50:53], off
	v_pk_mul_f32 v[46:47], v[46:47], v[54:55]
	s_nop 0
	v_mul_f32_e32 v50, 0xbfb8aa3b, v48
	v_mul_f32_e32 v51, 0xbfb8aa3b, v49
	v_exp_f32_e32 v50, v50
	v_exp_f32_e32 v51, v51
	v_pk_mul_f32 v[38:39], v[46:47], v[38:39]
	v_add_f32_e32 v46, 1.0, v50
	v_add_f32_e32 v47, 1.0, v51
	v_mul_f32_e32 v50, 0xbfb8aa3b, v42
	v_mul_f32_e32 v51, 0xbfb8aa3b, v43
	v_rcp_f32_e32 v46, v46
	v_rcp_f32_e32 v47, v47
	v_exp_f32_e32 v50, v50
	v_exp_f32_e32 v51, v51
	v_pk_mul_f32 v[46:47], v[48:49], v[46:47]
	v_add_f32_e32 v48, 1.0, v50
	v_add_f32_e32 v49, 1.0, v51
	v_mul_f32_e32 v50, 0xbfb8aa3b, v44
	v_mul_f32_e32 v51, 0xbfb8aa3b, v45
	v_exp_f32_e32 v50, v50
	v_exp_f32_e32 v51, v51
	v_rcp_f32_e32 v48, v48
	v_rcp_f32_e32 v49, v49
	v_add_f32_e32 v50, 1.0, v50
	v_add_f32_e32 v51, 1.0, v51
	v_rcp_f32_e32 v50, v50
	v_rcp_f32_e32 v51, v51
	v_pk_mul_f32 v[42:43], v[42:43], v[48:49]
	v_pk_mul_f32 v[40:41], v[46:47], v[40:41]
	v_pk_mul_f32 v[42:43], v[42:43], v[34:35]
	v_pk_mul_f32 v[34:35], v[44:45], v[50:51]
	v_lshl_add_u64 v[46:47], v[156:157], 0, v[146:147]
	v_pk_mul_f32 v[44:45], v[34:35], v[36:37]
	v_mul_f32_e32 v35, 0xbfb8aa3b, v30
	v_exp_f32_e32 v36, v35
	v_mul_f32_e32 v35, 0xbfb8aa3b, v31
	v_exp_f32_e32 v37, v35
	v_cvt_pk_bf16_f32 v34, v38, v39
	v_add_f32_e32 v36, 1.0, v36
	v_rcp_f32_e32 v38, v36
	v_add_f32_e32 v36, 1.0, v37
	v_cvt_pk_bf16_f32 v35, v40, v41
	v_rcp_f32_e32 v39, v36
	v_cvt_pk_bf16_f32 v36, v42, v43
	v_cvt_pk_bf16_f32 v37, v44, v45
	global_store_dwordx4 v[46:47], v[34:37], off
	v_pk_mul_f32 v[30:31], v[30:31], v[38:39]
	s_nop 0
	v_mul_f32_e32 v34, 0xbfb8aa3b, v32
	v_mul_f32_e32 v35, 0xbfb8aa3b, v33
	v_exp_f32_e32 v34, v34
	v_exp_f32_e32 v35, v35
	v_pk_mul_f32 v[22:23], v[30:31], v[22:23]
	v_add_f32_e32 v30, 1.0, v34
	v_add_f32_e32 v31, 1.0, v35
	v_mul_f32_e32 v34, 0xbfb8aa3b, v26
	v_mul_f32_e32 v35, 0xbfb8aa3b, v27
	v_rcp_f32_e32 v30, v30
	v_rcp_f32_e32 v31, v31
	v_exp_f32_e32 v34, v34
	v_exp_f32_e32 v35, v35
	v_pk_mul_f32 v[30:31], v[32:33], v[30:31]
	v_add_f32_e32 v32, 1.0, v34
	v_add_f32_e32 v33, 1.0, v35
	v_mul_f32_e32 v34, 0xbfb8aa3b, v28
	v_mul_f32_e32 v35, 0xbfb8aa3b, v29
	v_exp_f32_e32 v34, v34
	v_exp_f32_e32 v35, v35
	v_rcp_f32_e32 v32, v32
	v_rcp_f32_e32 v33, v33
	v_add_f32_e32 v34, 1.0, v34
	v_add_f32_e32 v35, 1.0, v35
	v_rcp_f32_e32 v34, v34
	v_rcp_f32_e32 v35, v35
	v_pk_mul_f32 v[26:27], v[26:27], v[32:33]
	v_pk_mul_f32 v[24:25], v[30:31], v[24:25]
	v_pk_mul_f32 v[26:27], v[26:27], v[18:19]
	v_pk_mul_f32 v[18:19], v[28:29], v[34:35]
	v_lshl_add_u64 v[30:31], v[156:157], 0, v[148:149]
	v_pk_mul_f32 v[28:29], v[18:19], v[20:21]
	v_mul_f32_e32 v19, 0xbfb8aa3b, v14
	v_exp_f32_e32 v20, v19
	v_mul_f32_e32 v19, 0xbfb8aa3b, v15
	v_exp_f32_e32 v21, v19
	v_cvt_pk_bf16_f32 v18, v22, v23
	v_add_f32_e32 v20, 1.0, v20
	v_rcp_f32_e32 v22, v20
	v_add_f32_e32 v20, 1.0, v21
	v_cvt_pk_bf16_f32 v19, v24, v25
	v_rcp_f32_e32 v23, v20
	v_cvt_pk_bf16_f32 v20, v26, v27
	v_cvt_pk_bf16_f32 v21, v28, v29
	global_store_dwordx4 v[30:31], v[18:21], off
	v_pk_mul_f32 v[14:15], v[14:15], v[22:23]
	s_nop 0
	v_mul_f32_e32 v18, 0xbfb8aa3b, v16
	v_mul_f32_e32 v19, 0xbfb8aa3b, v17
	v_exp_f32_e32 v18, v18
	v_exp_f32_e32 v19, v19
	v_pk_mul_f32 v[6:7], v[14:15], v[6:7]
	v_add_f32_e32 v14, 1.0, v18
	v_add_f32_e32 v15, 1.0, v19
	v_mul_f32_e32 v18, 0xbfb8aa3b, v10
	v_mul_f32_e32 v19, 0xbfb8aa3b, v11
	v_rcp_f32_e32 v14, v14
	v_rcp_f32_e32 v15, v15
	v_exp_f32_e32 v18, v18
	v_exp_f32_e32 v19, v19
	v_pk_mul_f32 v[14:15], v[16:17], v[14:15]
	v_add_f32_e32 v16, 1.0, v18
	v_add_f32_e32 v17, 1.0, v19
	v_mul_f32_e32 v18, 0xbfb8aa3b, v12
	v_mul_f32_e32 v19, 0xbfb8aa3b, v13
	v_exp_f32_e32 v18, v18
	v_exp_f32_e32 v19, v19
	v_rcp_f32_e32 v16, v16
	v_rcp_f32_e32 v17, v17
	v_add_f32_e32 v18, 1.0, v18
	v_add_f32_e32 v19, 1.0, v19
	v_rcp_f32_e32 v18, v18
	v_rcp_f32_e32 v19, v19
	v_pk_mul_f32 v[10:11], v[10:11], v[16:17]
	v_pk_mul_f32 v[8:9], v[14:15], v[8:9]
	v_pk_mul_f32 v[10:11], v[10:11], v[2:3]
	v_pk_mul_f32 v[2:3], v[12:13], v[18:19]
	v_lshl_add_u64 v[14:15], v[156:157], 0, v[150:151]
	v_pk_mul_f32 v[12:13], v[2:3], v[4:5]
	v_cvt_pk_bf16_f32 v2, v6, v7
	v_cvt_pk_bf16_f32 v3, v8, v9
	v_cvt_pk_bf16_f32 v4, v10, v11
	v_cvt_pk_bf16_f32 v5, v12, v13
	global_store_dwordx4 v[14:15], v[2:5], off
	s_cbranch_vccnz .LBB0_118
	s_branch .LBB0_117
.LBB0_128:
	s_and_b64 vcc, exec, s[4:5]
	s_cbranch_vccz .Lna_ffn1
	s_barrier

; #define PG8_STAGE(bufoff, gbase, voff) do { _Pragma("unroll") for (int _i = 0; _i < 2; ++_i) \
;         __builtin_amdgcn_global_load_lds((const unsigned*)((const char*)(gbase) + (voff)[_i]), (LAS unsigned*)(lds + (bufoff) + ldsw + _i * 8192), 16, 0, 0); } while (0)
; #define PG8_LDA(dst, b, h) do { _Pragma("unroll") for (int m = 0; m < 4; ++m) _Pragma("unroll") for (int k = 0; k < 2; ++k) dst[m][k] = *(const LAS bf16x8*)(lds + PG8_SA(b, h) + aoff + m * 2048 + k * 1024); } while (0)
; #define PG8_LDB(dst, b, h) do { _Pragma("unroll") for (int n = 0; n < 2; ++n) _Pragma("unroll") for (int k = 0; k < 2; ++k) dst[n][k] = *(const LAS bf16x8*)(lds + PG8_SB(b, h) + boff + n * 2048 + k * 1024); } while (0)
; #define PG8_MMA(ai, bj, At, Bt) do { __builtin_amdgcn_s_setprio(1); _Pragma("unroll") for (int m = 0; m < 4; ++m) _Pragma("unroll") for (int n = 0; n < 2; ++n) _Pragma("unroll") for (int k = 0; k < 2; ++k) \
;         acc[ai][bj][m][n] = __builtin_amdgcn_mfma_f32_16x16x32_bf16(Bt[n][k], At[m][k], acc[ai][bj][m][n], 0, 0, 0); __builtin_amdgcn_s_setprio(0); } while (0)
; #define PG8_WAIT_V(n) asm volatile("s_waitcnt vmcnt(" #n ")" ::: "memory")
; #define PG8_WAIT_L(n) asm volatile("s_waitcnt lgkmcnt(" #n ")" ::: "memory")
; #define PG8_BAR __builtin_amdgcn_s_barrier()
; #define PG8_SCHED __builtin_amdgcn_sched_barrier(0)
; template <class Epi, bool ALIGN_EPI, bool ASLOT = false>
; __device__ __forceinline__ void gemm_phase(LAS unsigned char* lds, const Gemm g, const Sched& S, const Epi& E) {
;     ...
;             const bool last = (t == nt - 2);
;             const char* a1 = cA + (size_t)(t + 1) * kstep;
;             const char* a2 = last ? nA : cA + (size_t)(t + 2) * kstep; const char* b2 = last ? nB : cB + (size_t)(t + 2) * kstep;
;             const char* a3 = a2 + kstep; const char* b3 = b2 + kstep;
;             PG8_LDB(B0, 0, 0); PG8_LDB(B1, 0, 1); PG8_SCHED; PG8_LDA(At, 0, 0); PG8_STAGE(PG8_SA(1, 1), a1 + hstep, voffA);
;             PG8_WAIT_V(8); PG8_WAIT_L(0); PG8_BAR; PG8_MMA(0, 0, At, B0); PG8_MMA(0, 1, At, B1); PG8_BAR; PG8_SCHED;
;             PG8_LDA(At, 0, 1); PG8_STAGE(PG8_SB(0, 0), b2, voffB); PG8_STAGE(PG8_SB(0, 1), b2 + hstep, voffB); PG8_STAGE(PG8_SA(0, 0), a2, voffA);
;             PG8_WAIT_V(8); PG8_WAIT_L(0); PG8_BAR; PG8_MMA(1, 0, At, B0); PG8_MMA(1, 1, At, B1); PG8_BAR; PG8_SCHED;
.LBB0_300:
	v_add_u32_e32 v0, s28, v177
	ds_read_b128 v[130:133], v0
	ds_read_b128 v[134:137], v0 offset:1024
	ds_read_b128 v[138:141], v0 offset:2048
	ds_read_b128 v[142:145], v0 offset:3072
	v_add_u32_e32 v0, s33, v177
	ds_read_b128 v[158:161], v0
	ds_read_b128 v[162:165], v0 offset:1024
	ds_read_b128 v[166:169], v0 offset:2048
	ds_read_b128 v[170:173], v0 offset:3072
	s_add_u32 s14, s0, 0xfffc0080
	s_addc_u32 s15, s1, -1
	s_cmp_eq_u32 s57, 12
	s_cselect_b32 s19, s3, s15
	s_cselect_b32 s18, s24, s14
	s_cselect_b32 s15, s25, s45
	s_cselect_b32 s14, s41, s43
	v_lshl_add_u64 v[174:175], s[0:1], 0, v[154:155]
	s_add_i32 m0, s50, 0xc000
	ds_read_b128 v[182:185], v180
	ds_read_b128 v[186:189], v180 offset:1024
	ds_read_b128 v[190:193], v180 offset:2048
	ds_read_b128 v[194:197], v180 offset:3072
	ds_read_b128 v[198:201], v180 offset:4096
	ds_read_b128 v[202:205], v180 offset:5120
	ds_read_b128 v[206:209], v180 offset:6144
	ds_read_b128 v[210:213], v180 offset:7168
	global_load_lds_dwordx4 v[174:175], off
	v_lshl_add_u64 v[174:175], s[0:1], 0, v[156:157]
	s_add_i32 m0, s50, 0xe000
	s_nop 0
	global_load_lds_dwordx4 v[174:175], off
	s_waitcnt vmcnt(8)
	s_waitcnt lgkmcnt(0)
	s_barrier
	s_setprio 1
	s_waitcnt lgkmcnt(0)
	v_mfma_f32_16x16x32_bf16 v[126:129], v[130:133], v[182:185], v[126:129]
	v_mfma_f32_16x16x32_bf16 v[122:125], v[138:141], v[182:185], v[122:125]
	v_mfma_f32_16x16x32_bf16 v[110:113], v[130:133], v[190:193], v[110:113]
	v_mfma_f32_16x16x32_bf16 v[106:109], v[138:141], v[190:193], v[106:109]
	v_mfma_f32_16x16x32_bf16 v[94:97], v[130:133], v[198:201], v[94:97]
	v_mfma_f32_16x16x32_bf16 v[90:93], v[138:141], v[198:201], v[90:93]
	v_mfma_f32_16x16x32_bf16 v[78:81], v[130:133], v[206:209], v[78:81]
	v_mfma_f32_16x16x32_bf16 v[74:77], v[138:141], v[206:209], v[74:77]
	v_mfma_f32_16x16x32_bf16 v[126:129], v[134:137], v[186:189], v[126:129]
	v_mfma_f32_16x16x32_bf16 v[122:125], v[142:145], v[186:189], v[122:125]
	v_mfma_f32_16x16x32_bf16 v[110:113], v[134:137], v[194:197], v[110:113]
	v_mfma_f32_16x16x32_bf16 v[106:109], v[142:145], v[194:197], v[106:109]
	v_mfma_f32_16x16x32_bf16 v[94:97], v[134:137], v[202:205], v[94:97]
	v_mfma_f32_16x16x32_bf16 v[90:93], v[142:145], v[202:205], v[90:93]
	v_mfma_f32_16x16x32_bf16 v[78:81], v[134:137], v[210:213], v[78:81]
	v_mfma_f32_16x16x32_bf16 v[74:77], v[142:145], v[210:213], v[74:77]
	s_setprio 0
	s_setprio 1
	v_mfma_f32_16x16x32_bf16 v[118:121], v[158:161], v[182:185], v[118:121]
	v_mfma_f32_16x16x32_bf16 v[114:117], v[166:169], v[182:185], v[114:117]
	v_mfma_f32_16x16x32_bf16 v[102:105], v[158:161], v[190:193], v[102:105]
	v_mfma_f32_16x16x32_bf16 v[98:101], v[166:169], v[190:193], v[98:101]
	v_mfma_f32_16x16x32_bf16 v[86:89], v[158:161], v[198:201], v[86:89]
	v_mfma_f32_16x16x32_bf16 v[82:85], v[166:169], v[198:201], v[82:85]
	v_mfma_f32_16x16x32_bf16 v[70:73], v[158:161], v[206:209], v[70:73]
	v_mfma_f32_16x16x32_bf16 v[66:69], v[166:169], v[206:209], v[66:69]
	v_mfma_f32_16x16x32_bf16 v[118:121], v[162:165], v[186:189], v[118:121]
	v_mfma_f32_16x16x32_bf16 v[114:117], v[170:173], v[186:189], v[114:117]
	v_mfma_f32_16x16x32_bf16 v[102:105], v[162:165], v[194:197], v[102:105]
	v_mfma_f32_16x16x32_bf16 v[98:101], v[170:173], v[194:197], v[98:101]
	v_mfma_f32_16x16x32_bf16 v[86:89], v[162:165], v[202:205], v[86:89]
	v_mfma_f32_16x16x32_bf16 v[82:85], v[170:173], v[202:205], v[82:85]
	v_mfma_f32_16x16x32_bf16 v[70:73], v[162:165], v[210:213], v[70:73]
	v_mfma_f32_16x16x32_bf16 v[66:69], v[170:173], v[210:213], v[66:69]
	s_setprio 0
	s_barrier
	s_add_i32 s22, s28, s27
	v_lshl_add_u64 v[174:175], s[14:15], 0, v[148:149]
	s_mov_b32 m0, s22
	ds_read_b128 v[182:185], v180 offset:16384
	ds_read_b128 v[186:189], v180 offset:17408
	ds_read_b128 v[190:193], v180 offset:18432
	ds_read_b128 v[194:197], v180 offset:19456
	ds_read_b128 v[198:201], v180 offset:20480
	ds_read_b128 v[202:205], v180 offset:21504
	ds_read_b128 v[206:209], v180 offset:22528
	ds_read_b128 v[210:213], v180 offset:23552
	global_load_lds_dwordx4 v[174:175], off
	s_add_i32 m0, s22, 0x2000
	s_add_u32 s22, s14, 0x40000
	v_lshl_add_u64 v[214:215], s[14:15], 0, v[152:153]
	s_addc_u32 s23, s15, 0
	s_add_i32 s30, s33, s27
	global_load_lds_dwordx4 v[214:215], off
	v_lshl_add_u64 v[220:221], s[22:23], 0, v[148:149]
	s_mov_b32 m0, s30
	v_lshl_add_u64 v[222:223], s[18:19], 0, v[150:151]
	global_load_lds_dwordx4 v[220:221], off
	v_lshl_add_u64 v[220:221], s[22:23], 0, v[152:153]
	s_add_i32 m0, s30, 0x2000
	s_nop 0
	global_load_lds_dwordx4 v[220:221], off
	v_lshl_add_u64 v[220:221], s[18:19], 0, v[146:147]
	s_mov_b32 m0, s50
	s_nop 0
	global_load_lds_dwordx4 v[220:221], off
	s_mov_b32 m0, s51
	s_nop 0
	global_load_lds_dwordx4 v[222:223], off
	s_waitcnt vmcnt(8)
	s_waitcnt lgkmcnt(0)
	s_barrier
; #define PG8_STAGE(bufoff, gbase, voff) do { _Pragma("unroll") for (int _i = 0; _i < 2; ++_i) \
;         __builtin_amdgcn_global_load_lds((const unsigned*)((const char*)(gbase) + (voff)[_i]), (LAS unsigned*)(lds + (bufoff) + ldsw + _i * 8192), 16, 0, 0); } while (0)
; #define PG8_LDA(dst, b, h) do { _Pragma("unroll") for (int m = 0; m < 4; ++m) _Pragma("unroll") for (int k = 0; k < 2; ++k) dst[m][k] = *(const LAS bf16x8*)(lds + PG8_SA(b, h) + aoff + m * 2048 + k * 1024); } while (0)
; #define PG8_LDB(dst, b, h) do { _Pragma("unroll") for (int n = 0; n < 2; ++n) _Pragma("unroll") for (int k = 0; k < 2; ++k) dst[n][k] = *(const LAS bf16x8*)(lds + PG8_SB(b, h) + boff + n * 2048 + k * 1024); } while (0)
; #define PG8_MMA(ai, bj, At, Bt) do { __builtin_amdgcn_s_setprio(1); _Pragma("unroll") for (int m = 0; m < 4; ++m) _Pragma("unroll") for (int n = 0; n < 2; ++n) _Pragma("unroll") for (int k = 0; k < 2; ++k) \
;         acc[ai][bj][m][n] = __builtin_amdgcn_mfma_f32_16x16x32_bf16(Bt[n][k], At[m][k], acc[ai][bj][m][n], 0, 0, 0); __builtin_amdgcn_s_setprio(0); } while (0)
; #define PG8_WAIT_V(n) asm volatile("s_waitcnt vmcnt(" #n ")" ::: "memory")
; #define PG8_WAIT_L(n) asm volatile("s_waitcnt lgkmcnt(" #n ")" ::: "memory")
; #define PG8_BAR __builtin_amdgcn_s_barrier()
; #define PG8_SCHED __builtin_amdgcn_sched_barrier(0)
; template <class Epi, bool ALIGN_EPI, bool ASLOT = false>
; __device__ __forceinline__ void gemm_phase(LAS unsigned char* lds, const Gemm g, const Sched& S, const Epi& E) {
;     ...
;             PG8_WAIT_V(8); PG8_WAIT_L(0); PG8_BAR; PG8_MMA(1, 0, At, B0); PG8_MMA(1, 1, At, B1); PG8_BAR; PG8_SCHED;
;             PG8_LDB(B0, 1, 0); PG8_LDB(B1, 1, 1); PG8_SCHED; PG8_LDA(At, 1, 0); PG8_STAGE(PG8_SA(0, 1), a2 + hstep, voffA);
;             PG8_WAIT_V(8); PG8_WAIT_L(0); PG8_BAR; PG8_MMA(0, 0, At, B0); PG8_MMA(0, 1, At, B1); PG8_BAR; PG8_SCHED;
	s_setprio 1
	s_waitcnt lgkmcnt(0)
	v_mfma_f32_16x16x32_bf16 v[62:65], v[130:133], v[182:185], v[62:65]
	v_mfma_f32_16x16x32_bf16 v[58:61], v[138:141], v[182:185], v[58:61]
	v_mfma_f32_16x16x32_bf16 v[46:49], v[130:133], v[190:193], v[46:49]
	v_mfma_f32_16x16x32_bf16 v[42:45], v[138:141], v[190:193], v[42:45]
	v_mfma_f32_16x16x32_bf16 v[30:33], v[130:133], v[198:201], v[30:33]
	v_mfma_f32_16x16x32_bf16 v[26:29], v[138:141], v[198:201], v[26:29]
	v_mfma_f32_16x16x32_bf16 v[14:17], v[130:133], v[206:209], v[14:17]
	v_mfma_f32_16x16x32_bf16 v[10:13], v[138:141], v[206:209], v[10:13]
	v_mfma_f32_16x16x32_bf16 v[62:65], v[134:137], v[186:189], v[62:65]
	v_mfma_f32_16x16x32_bf16 v[58:61], v[142:145], v[186:189], v[58:61]
	v_mfma_f32_16x16x32_bf16 v[46:49], v[134:137], v[194:197], v[46:49]
	v_mfma_f32_16x16x32_bf16 v[42:45], v[142:145], v[194:197], v[42:45]
	v_mfma_f32_16x16x32_bf16 v[30:33], v[134:137], v[202:205], v[30:33]
	v_mfma_f32_16x16x32_bf16 v[26:29], v[142:145], v[202:205], v[26:29]
	v_mfma_f32_16x16x32_bf16 v[14:17], v[134:137], v[210:213], v[14:17]
	v_mfma_f32_16x16x32_bf16 v[10:13], v[142:145], v[210:213], v[10:13]
	s_setprio 0
	s_setprio 1
	v_mfma_f32_16x16x32_bf16 v[54:57], v[158:161], v[182:185], v[54:57]
	v_mfma_f32_16x16x32_bf16 v[50:53], v[166:169], v[182:185], v[50:53]
	v_mfma_f32_16x16x32_bf16 v[38:41], v[158:161], v[190:193], v[38:41]
	v_mfma_f32_16x16x32_bf16 v[34:37], v[166:169], v[190:193], v[34:37]
	v_mfma_f32_16x16x32_bf16 v[22:25], v[158:161], v[198:201], v[22:25]
	v_mfma_f32_16x16x32_bf16 v[18:21], v[166:169], v[198:201], v[18:21]
	v_mfma_f32_16x16x32_bf16 v[6:9], v[158:161], v[206:209], v[6:9]
	v_mfma_f32_16x16x32_bf16 v[2:5], v[166:169], v[206:209], v[2:5]
	v_mfma_f32_16x16x32_bf16 v[54:57], v[162:165], v[186:189], v[54:57]
	v_mfma_f32_16x16x32_bf16 v[50:53], v[170:173], v[186:189], v[50:53]
	v_mfma_f32_16x16x32_bf16 v[38:41], v[162:165], v[194:197], v[38:41]
	v_mfma_f32_16x16x32_bf16 v[34:37], v[170:173], v[194:197], v[34:37]
	v_mfma_f32_16x16x32_bf16 v[22:25], v[162:165], v[202:205], v[22:25]
	v_mfma_f32_16x16x32_bf16 v[18:21], v[170:173], v[202:205], v[18:21]
	v_mfma_f32_16x16x32_bf16 v[6:9], v[162:165], v[210:213], v[6:9]
	v_mfma_f32_16x16x32_bf16 v[2:5], v[170:173], v[210:213], v[2:5]
	s_setprio 0
	s_barrier
	v_add_u32_e32 v0, s29, v177
	ds_read_b128 v[130:133], v0
	ds_read_b128 v[134:137], v0 offset:1024
	ds_read_b128 v[138:141], v0 offset:2048
	ds_read_b128 v[142:145], v0 offset:3072
	v_add_u32_e32 v0, s26, v177
	ds_read_b128 v[158:161], v0
	ds_read_b128 v[162:165], v0 offset:1024
	ds_read_b128 v[166:169], v0 offset:2048
	ds_read_b128 v[170:173], v0 offset:3072
	s_add_u32 s18, s18, 0x40000
	s_addc_u32 s19, s19, 0
	s_mov_b32 m0, s52
	v_lshl_add_u64 v[232:233], s[18:19], 0, v[146:147]
	ds_read_b128 v[182:185], v180 offset:32768
	ds_read_b128 v[186:189], v180 offset:33792
	ds_read_b128 v[190:193], v180 offset:34816
	ds_read_b128 v[194:197], v180 offset:35840
	ds_read_b128 v[198:201], v180 offset:36864
	ds_read_b128 v[202:205], v180 offset:37888
	ds_read_b128 v[206:209], v180 offset:38912
	ds_read_b128 v[210:213], v180 offset:39936
	global_load_lds_dwordx4 v[232:233], off
	v_lshl_add_u64 v[232:233], s[18:19], 0, v[150:151]
	s_mov_b32 m0, s53
	s_nop 0
	global_load_lds_dwordx4 v[232:233], off
	s_waitcnt vmcnt(8)
	s_waitcnt lgkmcnt(0)
	s_barrier
	s_setprio 1
	s_waitcnt lgkmcnt(0)
	v_mfma_f32_16x16x32_bf16 v[126:129], v[130:133], v[182:185], v[126:129]
	v_mfma_f32_16x16x32_bf16 v[122:125], v[138:141], v[182:185], v[122:125]
	v_mfma_f32_16x16x32_bf16 v[110:113], v[130:133], v[190:193], v[110:113]
	v_mfma_f32_16x16x32_bf16 v[106:109], v[138:141], v[190:193], v[106:109]
	v_mfma_f32_16x16x32_bf16 v[94:97], v[130:133], v[198:201], v[94:97]
	v_mfma_f32_16x16x32_bf16 v[90:93], v[138:141], v[198:201], v[90:93]
	v_mfma_f32_16x16x32_bf16 v[78:81], v[130:133], v[206:209], v[78:81]
	v_mfma_f32_16x16x32_bf16 v[74:77], v[138:141], v[206:209], v[74:77]
	v_mfma_f32_16x16x32_bf16 v[126:129], v[134:137], v[186:189], v[126:129]
	v_mfma_f32_16x16x32_bf16 v[122:125], v[142:145], v[186:189], v[122:125]
	v_mfma_f32_16x16x32_bf16 v[110:113], v[134:137], v[194:197], v[110:113]
	v_mfma_f32_16x16x32_bf16 v[106:109], v[142:145], v[194:197], v[106:109]
	v_mfma_f32_16x16x32_bf16 v[94:97], v[134:137], v[202:205], v[94:97]
	v_mfma_f32_16x16x32_bf16 v[90:93], v[142:145], v[202:205], v[90:93]
	v_mfma_f32_16x16x32_bf16 v[78:81], v[134:137], v[210:213], v[78:81]
	v_mfma_f32_16x16x32_bf16 v[74:77], v[142:145], v[210:213], v[74:77]
	s_setprio 0
	s_setprio 1
	v_mfma_f32_16x16x32_bf16 v[118:121], v[158:161], v[182:185], v[118:121]
	v_mfma_f32_16x16x32_bf16 v[114:117], v[166:169], v[182:185], v[114:117]
	v_mfma_f32_16x16x32_bf16 v[102:105], v[158:161], v[190:193], v[102:105]
	v_mfma_f32_16x16x32_bf16 v[98:101], v[166:169], v[190:193], v[98:101]
	v_mfma_f32_16x16x32_bf16 v[86:89], v[158:161], v[198:201], v[86:89]
	v_mfma_f32_16x16x32_bf16 v[82:85], v[166:169], v[198:201], v[82:85]
	v_mfma_f32_16x16x32_bf16 v[70:73], v[158:161], v[206:209], v[70:73]
	v_mfma_f32_16x16x32_bf16 v[66:69], v[166:169], v[206:209], v[66:69]
	v_mfma_f32_16x16x32_bf16 v[118:121], v[162:165], v[186:189], v[118:121]
	v_mfma_f32_16x16x32_bf16 v[114:117], v[170:173], v[186:189], v[114:117]
	v_mfma_f32_16x16x32_bf16 v[102:105], v[162:165], v[194:197], v[102:105]
	v_mfma_f32_16x16x32_bf16 v[98:101], v[170:173], v[194:197], v[98:101]
	v_mfma_f32_16x16x32_bf16 v[86:89], v[162:165], v[202:205], v[86:89]
	v_mfma_f32_16x16x32_bf16 v[82:85], v[170:173], v[202:205], v[82:85]
	v_mfma_f32_16x16x32_bf16 v[70:73], v[162:165], v[210:213], v[70:73]
	v_mfma_f32_16x16x32_bf16 v[66:69], v[170:173], v[210:213], v[66:69]
	s_setprio 0
	s_barrier
; #define PG8_WAIT_V(n) asm volatile("s_waitcnt vmcnt(" #n ")" ::: "memory")
;     __device__ __forceinline__ void operator()(ACC_T, const Unit& u, int wr, int wc, int fr, int fq) const {
;         const int row0 = u.pm * BM + wr * 64 + fr, cw = wc * 32 + 8 * fq;
;         if (u.pn < 14) {
;             float sc = 1.f; if (u.pn < 2 || u.pn == 6 || u.pn == 7) sc = 0.125f * LOG2E; else if (u.pn >= 12) sc = 0.08838834764831845f * LOG2E;
;             const int col0 = u.pn * BM + cw;
; #pragma unroll
;             for (int ai = 0; ai < 2; ++ai)
; #pragma unroll
;                 for (int m = 0; m < 4; ++m) { bf16_t* rowp = P + (size_t)(row0 + ai * HALF + m * 16) * PW + col0;
; #pragma unroll
;                     for (int bj = 0; bj < 2; ++bj) { const f32x4 v0 = acc[ai][bj][m][0] * sc, v1 = acc[ai][bj][m][1] * sc;
;                         u32x4 w; w.x = cvt_pk_bf16(v0[0], v0[1]); w.y = cvt_pk_bf16(v0[2], v0[3]); w.z = cvt_pk_bf16(v1[0], v1[1]); w.w = cvt_pk_bf16(v1[2], v1[3]);
;                         *(u32x4*)(rowp + bj * HALF) = w;
;                         if (u.pn == 8 || u.pn == 9) {
;                             float q = (v0[0] * v0[0] + v0[1] * v0[1]) + (v0[2] * v0[2] + v0[3] * v0[3]) + (v1[0] * v1[0] + v1[1] * v1[1]) + (v1[2] * v1[2] + v1[3] * v1[3]);
;                             q += __shfl_xor(q, 16); q += __shfl_xor(q, 32);
;                             if (fq == 0) __hip_atomic_fetch_add(kn2 + (size_t)((u.pn - 8) * 4 + bj * 2 + (wc >> 1)) * T + (row0 + ai * HALF + m * 16), q, __ATOMIC_RELAXED, __HIP_MEMORY_SCOPE_AGENT); } } }
;         } else {
;             const int col0 = (u.pn - 14) * BM + cw;
;             f32x4 bv[2][2];
; #pragma unroll
;             for (int bj = 0; bj < 2; ++bj)
; #pragma unroll
;                 for (int n = 0; n < 2; ++n) bv[bj][n] = *(const f32x4*)(bias + col0 + bj * HALF + 4 * n);
; template <class Epi, bool ALIGN_EPI, bool ASLOT = false>
; __device__ __forceinline__ void gemm_phase(LAS unsigned char* lds, const Gemm g, const Sched& S, const Epi& E) {
;     ...
;             PG8_LDA(At, 1, 1); PG8_STAGE(PG8_SB(1, 0), b3, voffB); PG8_STAGE(PG8_SB(1, 1), b3 + hstep, voffB); PG8_STAGE(PG8_SA(1, 0), a3, voffA);
;             PG8_WAIT_V(8); PG8_WAIT_L(0); PG8_BAR; PG8_MMA(1, 0, At, B0); PG8_MMA(1, 1, At, B1); PG8_BAR; PG8_SCHED;
;         }
;         if constexpr (ALIGN_EPI) { if (wr == 0) PG8_BAR; }
	s_add_i32 s18, s29, s27
	v_lshl_add_u64 v[174:175], v[174:175], 0, s[16:17]
	s_mov_b32 m0, s18
	ds_read_b128 v[182:185], v180 offset:49152
	ds_read_b128 v[186:189], v180 offset:50176
	ds_read_b128 v[190:193], v180 offset:51200
	ds_read_b128 v[194:197], v180 offset:52224
	ds_read_b128 v[198:201], v180 offset:53248
	ds_read_b128 v[202:205], v180 offset:54272
	ds_read_b128 v[206:209], v180 offset:55296
	ds_read_b128 v[210:213], v180 offset:56320
	global_load_lds_dwordx4 v[174:175], off
	s_add_i32 m0, s18, 0x2000
	s_add_u32 s14, s14, 0x40080
	v_lshl_add_u64 v[174:175], v[214:215], 0, s[16:17]
	s_addc_u32 s15, s15, 0
	s_add_i32 s18, s26, s27
	global_load_lds_dwordx4 v[174:175], off
	v_lshl_add_u64 v[174:175], s[14:15], 0, v[148:149]
	s_mov_b32 m0, s18
	s_nop 0
	global_load_lds_dwordx4 v[174:175], off
	v_lshl_add_u64 v[174:175], s[14:15], 0, v[152:153]
	s_add_i32 m0, s18, 0x2000
	s_nop 0
	global_load_lds_dwordx4 v[174:175], off
	v_lshl_add_u64 v[174:175], v[220:221], 0, s[16:17]
	s_mov_b32 m0, s54
	s_nop 0
	global_load_lds_dwordx4 v[174:175], off
	v_lshl_add_u64 v[174:175], v[222:223], 0, s[16:17]
	s_mov_b32 m0, s55
	s_nop 0
	global_load_lds_dwordx4 v[174:175], off
	s_waitcnt vmcnt(8)
	s_waitcnt lgkmcnt(0)
	s_barrier
	s_setprio 1
	s_waitcnt lgkmcnt(0)
	v_mfma_f32_16x16x32_bf16 v[62:65], v[130:133], v[182:185], v[62:65]
	v_mfma_f32_16x16x32_bf16 v[58:61], v[138:141], v[182:185], v[58:61]
	v_mfma_f32_16x16x32_bf16 v[46:49], v[130:133], v[190:193], v[46:49]
	v_mfma_f32_16x16x32_bf16 v[42:45], v[138:141], v[190:193], v[42:45]
	v_mfma_f32_16x16x32_bf16 v[30:33], v[130:133], v[198:201], v[30:33]
	v_mfma_f32_16x16x32_bf16 v[26:29], v[138:141], v[198:201], v[26:29]
	v_mfma_f32_16x16x32_bf16 v[14:17], v[130:133], v[206:209], v[14:17]
	v_mfma_f32_16x16x32_bf16 v[10:13], v[138:141], v[206:209], v[10:13]
	v_mfma_f32_16x16x32_bf16 v[62:65], v[134:137], v[186:189], v[62:65]
	v_mfma_f32_16x16x32_bf16 v[58:61], v[142:145], v[186:189], v[58:61]
	v_mfma_f32_16x16x32_bf16 v[46:49], v[134:137], v[194:197], v[46:49]
	v_mfma_f32_16x16x32_bf16 v[42:45], v[142:145], v[194:197], v[42:45]
	v_mfma_f32_16x16x32_bf16 v[30:33], v[134:137], v[202:205], v[30:33]
	v_mfma_f32_16x16x32_bf16 v[26:29], v[142:145], v[202:205], v[26:29]
	v_mfma_f32_16x16x32_bf16 v[14:17], v[134:137], v[210:213], v[14:17]
	v_mfma_f32_16x16x32_bf16 v[10:13], v[142:145], v[210:213], v[10:13]
	s_setprio 0
	s_setprio 1
	v_mfma_f32_16x16x32_bf16 v[54:57], v[158:161], v[182:185], v[54:57]
	v_mfma_f32_16x16x32_bf16 v[50:53], v[166:169], v[182:185], v[50:53]
	v_mfma_f32_16x16x32_bf16 v[38:41], v[158:161], v[190:193], v[38:41]
	v_mfma_f32_16x16x32_bf16 v[34:37], v[166:169], v[190:193], v[34:37]
	v_mfma_f32_16x16x32_bf16 v[22:25], v[158:161], v[198:201], v[22:25]
	v_mfma_f32_16x16x32_bf16 v[18:21], v[166:169], v[198:201], v[18:21]
	v_mfma_f32_16x16x32_bf16 v[6:9], v[158:161], v[206:209], v[6:9]
	v_mfma_f32_16x16x32_bf16 v[2:5], v[166:169], v[206:209], v[2:5]
	v_mfma_f32_16x16x32_bf16 v[54:57], v[162:165], v[186:189], v[54:57]
	v_mfma_f32_16x16x32_bf16 v[50:53], v[170:173], v[186:189], v[50:53]
	v_mfma_f32_16x16x32_bf16 v[38:41], v[162:165], v[194:197], v[38:41]
	v_mfma_f32_16x16x32_bf16 v[34:37], v[170:173], v[194:197], v[34:37]
	v_mfma_f32_16x16x32_bf16 v[22:25], v[162:165], v[202:205], v[22:25]
	v_mfma_f32_16x16x32_bf16 v[18:21], v[170:173], v[202:205], v[18:21]
	v_mfma_f32_16x16x32_bf16 v[6:9], v[162:165], v[210:213], v[6:9]
	v_mfma_f32_16x16x32_bf16 v[2:5], v[170:173], v[210:213], v[2:5]
	s_setprio 0
	s_barrier
	s_add_i32 s57, s57, 2
	s_add_u32 s0, s0, 0x100
	s_addc_u32 s1, s1, 0
	s_add_u32 s43, s43, 0x100
	s_addc_u32 s45, s45, 0
	s_cmp_gt_u32 s57, 13
	s_cbranch_scc0 .LBB0_300
.LBB0_303:
	v_lshl_add_u32 v158, s2, 8, v176
	s_mov_b64 s[0:1], -1
	s_cmp_gt_i32 s40, 13
	v_or_b32_e32 v168, 16, v158
	v_or_b32_e32 v166, 32, v158
	v_or_b32_e32 v164, 48, v158
	v_add_u32_e32 v162, 0x80, v158
	v_add_u32_e32 v160, 0x90, v158
	s_cbranch_scc0 .LBB0_305
	v_lshl_add_u32 v0, s40, 8, v179
	v_lshl_add_u64 v[134:135], v[0:1], 2, s[10:11]
	global_load_dwordx4 v[138:141], v[134:135], off offset:16
	global_load_dwordx4 v[142:145], v[134:135], off
	global_load_dwordx4 v[130:133], v[134:135], off offset:528
	s_nop 0
	global_load_dwordx4 v[134:137], v[134:135], off offset:512
	v_lshlrev_b64 v[172:173], 1, v[0:1]
	v_readlane_b32 s0, v251, 58
	v_readlane_b32 s1, v251, 59
	s_movk_i32 s2, 0x1800
	s_waitcnt vmcnt(0)
; __device__ __forceinline__ unsigned cvt_pk_bf16(float lo, float hi) { f32x2 v = {lo, hi}; bf16x2_t b = __builtin_convertvector(v, bf16x2_t); return __builtin_bit_cast(unsigned, b); }
; __device__ __forceinline__ float fast_exp2(float x) { return __builtin_amdgcn_exp2f(x); }
; __device__ __forceinline__ float fast_rcp(float x) { return __builtin_amdgcn_rcpf(x); }
;     __device__ __forceinline__ void operator()(ACC_T, const Unit& u, int wr, int wc, int fr, int fq) const {
;     ...
;             for (int ai = 0; ai < 2; ++ai)
; #pragma unroll
;                 for (int m = 0; m < 4; ++m) { bf16_t* rowp = Gt + (size_t)(row0 + ai * HALF + m * 16) * GW + col0;
; #pragma unroll
;                     for (int bj = 0; bj < 2; ++bj) { float r[8];
; #pragma unroll
;                         for (int n = 0; n < 2; ++n)
; #pragma unroll
;                             for (int e = 0; e < 4; ++e) { const float x = acc[ai][bj][m][n][e] + bv[bj][n][e]; r[n * 4 + e] = fast_rcp(1.f + fast_exp2(-x * LOG2E)); }
;                         u32x4 w; w.x = cvt_pk_bf16(r[0], r[1]); w.y = cvt_pk_bf16(r[2], r[3]); w.z = cvt_pk_bf16(r[4], r[5]); w.w = cvt_pk_bf16(r[6], r[7]);
;                         *(u32x4*)(rowp + bj * HALF) = w; } }
	v_add_f32_e32 v165, v122, v138
	v_add_f32_e32 v0, v126, v142
	v_add_f32_e32 v159, v127, v143
	v_add_f32_e32 v161, v128, v144
	v_add_f32_e32 v163, v129, v145
	v_add_f32_e32 v167, v123, v139
	v_add_f32_e32 v169, v124, v140
	v_add_f32_e32 v181, v125, v141
	v_mul_f32_e32 v0, 0xbfb8aa3b, v0
	v_mul_f32_e32 v159, 0xbfb8aa3b, v159
	v_mul_f32_e32 v161, 0xbfb8aa3b, v161
	v_mul_f32_e32 v163, 0xbfb8aa3b, v163
	v_mul_f32_e32 v165, 0xbfb8aa3b, v165
	v_mul_f32_e32 v167, 0xbfb8aa3b, v167
	v_mul_f32_e32 v169, 0xbfb8aa3b, v169
	v_mul_f32_e32 v181, 0xbfb8aa3b, v181
	v_exp_f32_e32 v0, v0
	v_exp_f32_e32 v159, v159
	v_exp_f32_e32 v161, v161
	v_exp_f32_e32 v163, v163
	v_exp_f32_e32 v165, v165
	v_exp_f32_e32 v167, v167
	v_exp_f32_e32 v169, v169
	v_exp_f32_e32 v181, v181
	v_add_f32_e32 v0, 1.0, v0
	v_add_f32_e32 v159, 1.0, v159
	v_add_f32_e32 v161, 1.0, v161
	v_add_f32_e32 v163, 1.0, v163
	v_add_f32_e32 v165, 1.0, v165
	v_add_f32_e32 v167, 1.0, v167
	v_add_f32_e32 v169, 1.0, v169
	v_add_f32_e32 v181, 1.0, v181
	v_rcp_f32_e32 v0, v0
	v_rcp_f32_e32 v159, v159
	v_rcp_f32_e32 v161, v161
	v_rcp_f32_e32 v163, v163
	v_rcp_f32_e32 v165, v165
	v_rcp_f32_e32 v167, v167
	v_rcp_f32_e32 v169, v169
	v_rcp_f32_e32 v181, v181
	v_cvt_pk_bf16_f32 v182, v0, v159
	v_cvt_pk_bf16_f32 v183, v161, v163
	v_cvt_pk_bf16_f32 v184, v165, v167
	v_cvt_pk_bf16_f32 v185, v169, v181
	v_add_f32_e32 v0, v118, v134
	v_add_f32_e32 v159, v119, v135
	v_add_f32_e32 v161, v120, v136
	v_add_f32_e32 v163, v121, v137
	v_add_f32_e32 v165, v114, v130
	v_add_f32_e32 v167, v115, v131
	v_add_f32_e32 v169, v116, v132
	v_add_f32_e32 v181, v117, v133
	v_mul_f32_e32 v0, 0xbfb8aa3b, v0
	v_mul_f32_e32 v159, 0xbfb8aa3b, v159
	v_mul_f32_e32 v161, 0xbfb8aa3b, v161
	v_mul_f32_e32 v163, 0xbfb8aa3b, v163
	v_mul_f32_e32 v165, 0xbfb8aa3b, v165
	v_mul_f32_e32 v167, 0xbfb8aa3b, v167
	v_mul_f32_e32 v169, 0xbfb8aa3b, v169
	v_mul_f32_e32 v181, 0xbfb8aa3b, v181
	v_exp_f32_e32 v0, v0
	v_exp_f32_e32 v159, v159
	v_exp_f32_e32 v161, v161
	v_exp_f32_e32 v163, v163
	v_exp_f32_e32 v165, v165
	v_exp_f32_e32 v167, v167
	v_exp_f32_e32 v169, v169
	v_exp_f32_e32 v181, v181
	v_add_f32_e32 v0, 1.0, v0
	v_add_f32_e32 v159, 1.0, v159
	v_add_f32_e32 v161, 1.0, v161
	v_add_f32_e32 v163, 1.0, v163
	v_add_f32_e32 v165, 1.0, v165
	v_add_f32_e32 v167, 1.0, v167
	v_add_f32_e32 v169, 1.0, v169
	v_add_f32_e32 v181, 1.0, v181
	v_rcp_f32_e32 v0, v0
	v_rcp_f32_e32 v159, v159
	v_rcp_f32_e32 v161, v161
	v_rcp_f32_e32 v163, v163
	v_rcp_f32_e32 v165, v165
	v_rcp_f32_e32 v167, v167
	v_rcp_f32_e32 v169, v169
	v_rcp_f32_e32 v181, v181
	v_mov_b64_e32 v[170:171], s[0:1]
	v_mad_i64_i32 v[174:175], s[0:1], v158, s2, v[170:171]
	v_lshl_add_u64 v[174:175], v[174:175], 0, v[172:173]
	global_store_dwordx4 v[174:175], v[182:185], off
	s_nop 1
	v_cvt_pk_bf16_f32 v182, v0, v159
	v_cvt_pk_bf16_f32 v183, v161, v163
	v_cvt_pk_bf16_f32 v184, v165, v167
	v_cvt_pk_bf16_f32 v185, v169, v181
	v_add_f32_e32 v0, v110, v142
	v_add_f32_e32 v159, v111, v143
	v_add_f32_e32 v161, v112, v144
	v_add_f32_e32 v163, v113, v145
	v_add_f32_e32 v165, v106, v138
	v_add_f32_e32 v167, v107, v139
	v_add_f32_e32 v169, v108, v140
	v_add_f32_e32 v181, v109, v141
	v_mul_f32_e32 v0, 0xbfb8aa3b, v0
	v_mul_f32_e32 v159, 0xbfb8aa3b, v159
	v_mul_f32_e32 v161, 0xbfb8aa3b, v161
	v_mul_f32_e32 v163, 0xbfb8aa3b, v163
	v_mul_f32_e32 v165, 0xbfb8aa3b, v165
	v_mul_f32_e32 v167, 0xbfb8aa3b, v167
	v_mul_f32_e32 v169, 0xbfb8aa3b, v169
	v_mul_f32_e32 v181, 0xbfb8aa3b, v181
	v_exp_f32_e32 v0, v0
	v_exp_f32_e32 v159, v159
	v_exp_f32_e32 v161, v161
	v_exp_f32_e32 v163, v163
	v_exp_f32_e32 v165, v165
	v_exp_f32_e32 v167, v167
	v_exp_f32_e32 v169, v169
	v_exp_f32_e32 v181, v181
	v_add_f32_e32 v0, 1.0, v0
	v_add_f32_e32 v159, 1.0, v159
	v_add_f32_e32 v161, 1.0, v161
	v_add_f32_e32 v163, 1.0, v163
	v_add_f32_e32 v165, 1.0, v165
	v_add_f32_e32 v167, 1.0, v167
	v_add_f32_e32 v169, 1.0, v169
	v_add_f32_e32 v181, 1.0, v181
	v_rcp_f32_e32 v0, v0
	v_rcp_f32_e32 v159, v159
	v_rcp_f32_e32 v161, v161
	v_rcp_f32_e32 v163, v163
	v_rcp_f32_e32 v165, v165
	v_rcp_f32_e32 v167, v167
	v_rcp_f32_e32 v169, v169
	v_rcp_f32_e32 v181, v181
	global_store_dwordx4 v[174:175], v[182:185], off offset:256
	v_mad_i64_i32 v[174:175], s[0:1], v168, s2, v[170:171]
	s_nop 0
	v_cvt_pk_bf16_f32 v182, v0, v159
	v_cvt_pk_bf16_f32 v183, v161, v163
	v_cvt_pk_bf16_f32 v184, v165, v167
	v_cvt_pk_bf16_f32 v185, v169, v181
	v_add_f32_e32 v0, v102, v134
	v_add_f32_e32 v159, v103, v135
	v_add_f32_e32 v161, v104, v136
	v_add_f32_e32 v163, v105, v137
	v_add_f32_e32 v165, v98, v130
	v_add_f32_e32 v167, v99, v131
	v_add_f32_e32 v169, v100, v132
	v_add_f32_e32 v181, v101, v133
	v_mul_f32_e32 v0, 0xbfb8aa3b, v0
	v_mul_f32_e32 v159, 0xbfb8aa3b, v159
	v_mul_f32_e32 v161, 0xbfb8aa3b, v161
	v_mul_f32_e32 v163, 0xbfb8aa3b, v163
	v_mul_f32_e32 v165, 0xbfb8aa3b, v165
	v_mul_f32_e32 v167, 0xbfb8aa3b, v167
	v_mul_f32_e32 v169, 0xbfb8aa3b, v169
	v_mul_f32_e32 v181, 0xbfb8aa3b, v181
	v_exp_f32_e32 v0, v0
	v_exp_f32_e32 v159, v159
	v_exp_f32_e32 v161, v161
	v_exp_f32_e32 v163, v163
	v_exp_f32_e32 v165, v165
	v_exp_f32_e32 v167, v167
	v_exp_f32_e32 v169, v169
	v_exp_f32_e32 v181, v181
	v_add_f32_e32 v0, 1.0, v0
	v_add_f32_e32 v159, 1.0, v159
	v_add_f32_e32 v161, 1.0, v161
	v_add_f32_e32 v163, 1.0, v163
	v_add_f32_e32 v165, 1.0, v165
	v_add_f32_e32 v167, 1.0, v167
	v_add_f32_e32 v169, 1.0, v169
	v_add_f32_e32 v181, 1.0, v181
	v_rcp_f32_e32 v0, v0
	v_rcp_f32_e32 v159, v159
	v_rcp_f32_e32 v161, v161
	v_rcp_f32_e32 v163, v163
	v_rcp_f32_e32 v165, v165
	v_rcp_f32_e32 v167, v167
	v_rcp_f32_e32 v169, v169
	v_rcp_f32_e32 v181, v181
	v_lshl_add_u64 v[174:175], v[174:175], 0, v[172:173]
; __device__ __forceinline__ unsigned cvt_pk_bf16(float lo, float hi) { f32x2 v = {lo, hi}; bf16x2_t b = __builtin_convertvector(v, bf16x2_t); return __builtin_bit_cast(unsigned, b); }
; __device__ __forceinline__ float fast_exp2(float x) { return __builtin_amdgcn_exp2f(x); }
; __device__ __forceinline__ float fast_rcp(float x) { return __builtin_amdgcn_rcpf(x); }
;     __device__ __forceinline__ void operator()(ACC_T, const Unit& u, int wr, int wc, int fr, int fq) const {
;     ...
;             for (int ai = 0; ai < 2; ++ai)
; #pragma unroll
;                 for (int m = 0; m < 4; ++m) { bf16_t* rowp = Gt + (size_t)(row0 + ai * HALF + m * 16) * GW + col0;
; #pragma unroll
;                     for (int bj = 0; bj < 2; ++bj) { float r[8];
; #pragma unroll
;                         for (int n = 0; n < 2; ++n)
; #pragma unroll
;                             for (int e = 0; e < 4; ++e) { const float x = acc[ai][bj][m][n][e] + bv[bj][n][e]; r[n * 4 + e] = fast_rcp(1.f + fast_exp2(-x * LOG2E)); }
;                         u32x4 w; w.x = cvt_pk_bf16(r[0], r[1]); w.y = cvt_pk_bf16(r[2], r[3]); w.z = cvt_pk_bf16(r[4], r[5]); w.w = cvt_pk_bf16(r[6], r[7]);
;                         *(u32x4*)(rowp + bj * HALF) = w; } }
	global_store_dwordx4 v[174:175], v[182:185], off
	s_nop 1
	v_cvt_pk_bf16_f32 v182, v0, v159
	v_cvt_pk_bf16_f32 v183, v161, v163
	v_cvt_pk_bf16_f32 v184, v165, v167
	v_cvt_pk_bf16_f32 v185, v169, v181
	v_add_f32_e32 v0, v94, v142
	v_add_f32_e32 v159, v95, v143
	v_add_f32_e32 v161, v96, v144
	v_add_f32_e32 v163, v97, v145
	v_add_f32_e32 v165, v90, v138
	v_add_f32_e32 v167, v91, v139
	v_add_f32_e32 v169, v92, v140
	v_add_f32_e32 v181, v93, v141
	v_mul_f32_e32 v0, 0xbfb8aa3b, v0
	v_mul_f32_e32 v159, 0xbfb8aa3b, v159
	v_mul_f32_e32 v161, 0xbfb8aa3b, v161
	v_mul_f32_e32 v163, 0xbfb8aa3b, v163
	v_mul_f32_e32 v165, 0xbfb8aa3b, v165
	v_mul_f32_e32 v167, 0xbfb8aa3b, v167
	v_mul_f32_e32 v169, 0xbfb8aa3b, v169
	v_mul_f32_e32 v181, 0xbfb8aa3b, v181
	v_exp_f32_e32 v0, v0
	v_exp_f32_e32 v159, v159
	v_exp_f32_e32 v161, v161
	v_exp_f32_e32 v163, v163
	v_exp_f32_e32 v165, v165
	v_exp_f32_e32 v167, v167
	v_exp_f32_e32 v169, v169
	v_exp_f32_e32 v181, v181
	v_add_f32_e32 v0, 1.0, v0
	v_add_f32_e32 v159, 1.0, v159
	v_add_f32_e32 v161, 1.0, v161
	v_add_f32_e32 v163, 1.0, v163
	v_add_f32_e32 v165, 1.0, v165
	v_add_f32_e32 v167, 1.0, v167
	v_add_f32_e32 v169, 1.0, v169
	v_add_f32_e32 v181, 1.0, v181
	v_rcp_f32_e32 v0, v0
	v_rcp_f32_e32 v159, v159
	v_rcp_f32_e32 v161, v161
	v_rcp_f32_e32 v163, v163
	v_rcp_f32_e32 v165, v165
	v_rcp_f32_e32 v167, v167
	v_rcp_f32_e32 v169, v169
	v_rcp_f32_e32 v181, v181
	global_store_dwordx4 v[174:175], v[182:185], off offset:256
	v_mad_i64_i32 v[174:175], s[0:1], v166, s2, v[170:171]
	s_nop 0
	v_cvt_pk_bf16_f32 v182, v0, v159
	v_cvt_pk_bf16_f32 v183, v161, v163
	v_cvt_pk_bf16_f32 v184, v165, v167
	v_cvt_pk_bf16_f32 v185, v169, v181
	v_add_f32_e32 v0, v86, v134
	v_add_f32_e32 v159, v87, v135
	v_add_f32_e32 v161, v88, v136
	v_add_f32_e32 v163, v89, v137
	v_add_f32_e32 v165, v82, v130
	v_add_f32_e32 v167, v83, v131
	v_add_f32_e32 v169, v84, v132
	v_add_f32_e32 v181, v85, v133
	v_mul_f32_e32 v0, 0xbfb8aa3b, v0
	v_mul_f32_e32 v159, 0xbfb8aa3b, v159
	v_mul_f32_e32 v161, 0xbfb8aa3b, v161
	v_mul_f32_e32 v163, 0xbfb8aa3b, v163
	v_mul_f32_e32 v165, 0xbfb8aa3b, v165
	v_mul_f32_e32 v167, 0xbfb8aa3b, v167
	v_mul_f32_e32 v169, 0xbfb8aa3b, v169
	v_mul_f32_e32 v181, 0xbfb8aa3b, v181
	v_exp_f32_e32 v0, v0
	v_exp_f32_e32 v159, v159
	v_exp_f32_e32 v161, v161
	v_exp_f32_e32 v163, v163
	v_exp_f32_e32 v165, v165
	v_exp_f32_e32 v167, v167
	v_exp_f32_e32 v169, v169
	v_exp_f32_e32 v181, v181
	v_add_f32_e32 v0, 1.0, v0
	v_add_f32_e32 v159, 1.0, v159
	v_add_f32_e32 v161, 1.0, v161
	v_add_f32_e32 v163, 1.0, v163
	v_add_f32_e32 v165, 1.0, v165
	v_add_f32_e32 v167, 1.0, v167
	v_add_f32_e32 v169, 1.0, v169
	v_add_f32_e32 v181, 1.0, v181
	v_rcp_f32_e32 v0, v0
	v_rcp_f32_e32 v159, v159
	v_rcp_f32_e32 v161, v161
	v_rcp_f32_e32 v163, v163
	v_rcp_f32_e32 v165, v165
	v_rcp_f32_e32 v167, v167
	v_rcp_f32_e32 v169, v169
	v_rcp_f32_e32 v181, v181
	v_lshl_add_u64 v[174:175], v[174:175], 0, v[172:173]
	global_store_dwordx4 v[174:175], v[182:185], off
	s_nop 1
	v_cvt_pk_bf16_f32 v182, v0, v159
	v_cvt_pk_bf16_f32 v183, v161, v163
	v_cvt_pk_bf16_f32 v184, v165, v167
	v_cvt_pk_bf16_f32 v185, v169, v181
	v_add_f32_e32 v0, v78, v142
	v_add_f32_e32 v159, v79, v143
	v_add_f32_e32 v161, v80, v144
	v_add_f32_e32 v163, v81, v145
	v_add_f32_e32 v165, v74, v138
	v_add_f32_e32 v167, v75, v139
	v_add_f32_e32 v169, v76, v140
	v_add_f32_e32 v181, v77, v141
	v_mul_f32_e32 v0, 0xbfb8aa3b, v0
	v_mul_f32_e32 v159, 0xbfb8aa3b, v159
	v_mul_f32_e32 v161, 0xbfb8aa3b, v161
	v_mul_f32_e32 v163, 0xbfb8aa3b, v163
	v_mul_f32_e32 v165, 0xbfb8aa3b, v165
	v_mul_f32_e32 v167, 0xbfb8aa3b, v167
	v_mul_f32_e32 v169, 0xbfb8aa3b, v169
	v_mul_f32_e32 v181, 0xbfb8aa3b, v181
	v_exp_f32_e32 v0, v0
	v_exp_f32_e32 v159, v159
	v_exp_f32_e32 v161, v161
	v_exp_f32_e32 v163, v163
	v_exp_f32_e32 v165, v165
	v_exp_f32_e32 v167, v167
	v_exp_f32_e32 v169, v169
	v_exp_f32_e32 v181, v181
	v_add_f32_e32 v0, 1.0, v0
	v_add_f32_e32 v159, 1.0, v159
	v_add_f32_e32 v161, 1.0, v161
	v_add_f32_e32 v163, 1.0, v163
	v_add_f32_e32 v165, 1.0, v165
	v_add_f32_e32 v167, 1.0, v167
	v_add_f32_e32 v169, 1.0, v169
	v_add_f32_e32 v181, 1.0, v181
	v_rcp_f32_e32 v0, v0
	v_rcp_f32_e32 v159, v159
	v_rcp_f32_e32 v161, v161
	v_rcp_f32_e32 v163, v163
	v_rcp_f32_e32 v165, v165
	v_rcp_f32_e32 v167, v167
	v_rcp_f32_e32 v169, v169
	v_rcp_f32_e32 v181, v181
	global_store_dwordx4 v[174:175], v[182:185], off offset:256
	v_mad_i64_i32 v[174:175], s[0:1], v164, s2, v[170:171]
	s_nop 0
	v_cvt_pk_bf16_f32 v182, v0, v159
	v_cvt_pk_bf16_f32 v183, v161, v163
	v_cvt_pk_bf16_f32 v184, v165, v167
	v_cvt_pk_bf16_f32 v185, v169, v181
	v_add_f32_e32 v0, v70, v134
	v_add_f32_e32 v159, v71, v135
	v_add_f32_e32 v161, v72, v136
	v_add_f32_e32 v163, v73, v137
	v_add_f32_e32 v165, v66, v130
	v_add_f32_e32 v167, v67, v131
	v_add_f32_e32 v169, v68, v132
	v_add_f32_e32 v181, v69, v133
	v_mul_f32_e32 v0, 0xbfb8aa3b, v0
	v_mul_f32_e32 v159, 0xbfb8aa3b, v159
	v_mul_f32_e32 v161, 0xbfb8aa3b, v161
	v_mul_f32_e32 v163, 0xbfb8aa3b, v163
	v_mul_f32_e32 v165, 0xbfb8aa3b, v165
	v_mul_f32_e32 v167, 0xbfb8aa3b, v167
	v_mul_f32_e32 v169, 0xbfb8aa3b, v169
	v_mul_f32_e32 v181, 0xbfb8aa3b, v181
	v_exp_f32_e32 v0, v0
	v_exp_f32_e32 v159, v159
	v_exp_f32_e32 v161, v161
	v_exp_f32_e32 v163, v163
	v_exp_f32_e32 v165, v165
	v_exp_f32_e32 v167, v167
	v_exp_f32_e32 v169, v169
	v_exp_f32_e32 v181, v181
	v_add_f32_e32 v0, 1.0, v0
	v_add_f32_e32 v159, 1.0, v159
	v_add_f32_e32 v161, 1.0, v161
	v_add_f32_e32 v163, 1.0, v163
	v_add_f32_e32 v165, 1.0, v165
	v_add_f32_e32 v167, 1.0, v167
	v_add_f32_e32 v169, 1.0, v169
	v_add_f32_e32 v181, 1.0, v181
	v_rcp_f32_e32 v0, v0
	v_rcp_f32_e32 v159, v159
; __device__ __forceinline__ unsigned cvt_pk_bf16(float lo, float hi) { f32x2 v = {lo, hi}; bf16x2_t b = __builtin_convertvector(v, bf16x2_t); return __builtin_bit_cast(unsigned, b); }
; __device__ __forceinline__ float fast_exp2(float x) { return __builtin_amdgcn_exp2f(x); }
; __device__ __forceinline__ float fast_rcp(float x) { return __builtin_amdgcn_rcpf(x); }
;     __device__ __forceinline__ void operator()(ACC_T, const Unit& u, int wr, int wc, int fr, int fq) const {
;     ...
;             for (int ai = 0; ai < 2; ++ai)
; #pragma unroll
;                 for (int m = 0; m < 4; ++m) { bf16_t* rowp = Gt + (size_t)(row0 + ai * HALF + m * 16) * GW + col0;
; #pragma unroll
;                     for (int bj = 0; bj < 2; ++bj) { float r[8];
; #pragma unroll
;                         for (int n = 0; n < 2; ++n)
; #pragma unroll
;                             for (int e = 0; e < 4; ++e) { const float x = acc[ai][bj][m][n][e] + bv[bj][n][e]; r[n * 4 + e] = fast_rcp(1.f + fast_exp2(-x * LOG2E)); }
;                         u32x4 w; w.x = cvt_pk_bf16(r[0], r[1]); w.y = cvt_pk_bf16(r[2], r[3]); w.z = cvt_pk_bf16(r[4], r[5]); w.w = cvt_pk_bf16(r[6], r[7]);
;                         *(u32x4*)(rowp + bj * HALF) = w; } }
	v_rcp_f32_e32 v161, v161
	v_rcp_f32_e32 v163, v163
	v_rcp_f32_e32 v165, v165
	v_rcp_f32_e32 v167, v167
	v_rcp_f32_e32 v169, v169
	v_rcp_f32_e32 v181, v181
	v_lshl_add_u64 v[174:175], v[174:175], 0, v[172:173]
	global_store_dwordx4 v[174:175], v[182:185], off
	s_nop 1
	v_cvt_pk_bf16_f32 v182, v0, v159
	v_cvt_pk_bf16_f32 v183, v161, v163
	v_cvt_pk_bf16_f32 v184, v165, v167
	v_cvt_pk_bf16_f32 v185, v169, v181
	v_add_f32_e32 v0, v62, v142
	v_add_f32_e32 v159, v63, v143
	v_add_f32_e32 v161, v64, v144
	v_add_f32_e32 v163, v65, v145
	v_add_f32_e32 v165, v58, v138
	v_add_f32_e32 v167, v59, v139
	v_add_f32_e32 v169, v60, v140
	v_add_f32_e32 v181, v61, v141
	v_mul_f32_e32 v0, 0xbfb8aa3b, v0
	v_mul_f32_e32 v159, 0xbfb8aa3b, v159
	v_mul_f32_e32 v161, 0xbfb8aa3b, v161
	v_mul_f32_e32 v163, 0xbfb8aa3b, v163
	v_mul_f32_e32 v165, 0xbfb8aa3b, v165
	v_mul_f32_e32 v167, 0xbfb8aa3b, v167
	v_mul_f32_e32 v169, 0xbfb8aa3b, v169
	v_mul_f32_e32 v181, 0xbfb8aa3b, v181
	v_exp_f32_e32 v0, v0
	v_exp_f32_e32 v159, v159
	v_exp_f32_e32 v161, v161
	v_exp_f32_e32 v163, v163
	v_exp_f32_e32 v165, v165
	v_exp_f32_e32 v167, v167
	v_exp_f32_e32 v169, v169
	v_exp_f32_e32 v181, v181
	v_add_f32_e32 v0, 1.0, v0
	v_add_f32_e32 v159, 1.0, v159
	v_add_f32_e32 v161, 1.0, v161
	v_add_f32_e32 v163, 1.0, v163
	v_add_f32_e32 v165, 1.0, v165
	v_add_f32_e32 v167, 1.0, v167
	v_add_f32_e32 v169, 1.0, v169
	v_add_f32_e32 v181, 1.0, v181
	v_rcp_f32_e32 v0, v0
	v_rcp_f32_e32 v159, v159
	v_rcp_f32_e32 v161, v161
	v_rcp_f32_e32 v163, v163
	v_rcp_f32_e32 v165, v165
	v_rcp_f32_e32 v167, v167
	v_rcp_f32_e32 v169, v169
	v_rcp_f32_e32 v181, v181
	global_store_dwordx4 v[174:175], v[182:185], off offset:256
	v_mad_i64_i32 v[174:175], s[0:1], v162, s2, v[170:171]
	s_nop 0
	v_cvt_pk_bf16_f32 v182, v0, v159
	v_cvt_pk_bf16_f32 v183, v161, v163
	v_cvt_pk_bf16_f32 v184, v165, v167
	v_cvt_pk_bf16_f32 v185, v169, v181
	v_add_f32_e32 v0, v54, v134
	v_add_f32_e32 v159, v55, v135
	v_add_f32_e32 v161, v56, v136
	v_add_f32_e32 v163, v57, v137
	v_add_f32_e32 v165, v50, v130
	v_add_f32_e32 v167, v51, v131
	v_add_f32_e32 v169, v52, v132
	v_add_f32_e32 v181, v53, v133
	v_mul_f32_e32 v0, 0xbfb8aa3b, v0
	v_mul_f32_e32 v159, 0xbfb8aa3b, v159
	v_mul_f32_e32 v161, 0xbfb8aa3b, v161
	v_mul_f32_e32 v163, 0xbfb8aa3b, v163
	v_mul_f32_e32 v165, 0xbfb8aa3b, v165
	v_mul_f32_e32 v167, 0xbfb8aa3b, v167
	v_mul_f32_e32 v169, 0xbfb8aa3b, v169
	v_mul_f32_e32 v181, 0xbfb8aa3b, v181
	v_exp_f32_e32 v0, v0
	v_exp_f32_e32 v159, v159
	v_exp_f32_e32 v161, v161
	v_exp_f32_e32 v163, v163
	v_exp_f32_e32 v165, v165
	v_exp_f32_e32 v167, v167
	v_exp_f32_e32 v169, v169
	v_exp_f32_e32 v181, v181
	v_add_f32_e32 v0, 1.0, v0
	v_add_f32_e32 v159, 1.0, v159
	v_add_f32_e32 v161, 1.0, v161
	v_add_f32_e32 v163, 1.0, v163
	v_add_f32_e32 v165, 1.0, v165
	v_add_f32_e32 v167, 1.0, v167
	v_add_f32_e32 v169, 1.0, v169
	v_add_f32_e32 v181, 1.0, v181
	v_rcp_f32_e32 v0, v0
	v_rcp_f32_e32 v159, v159
	v_rcp_f32_e32 v161, v161
	v_rcp_f32_e32 v163, v163
	v_rcp_f32_e32 v165, v165
	v_rcp_f32_e32 v167, v167
	v_rcp_f32_e32 v169, v169
	v_rcp_f32_e32 v181, v181
	v_lshl_add_u64 v[174:175], v[174:175], 0, v[172:173]
	global_store_dwordx4 v[174:175], v[182:185], off
	s_nop 1
	v_cvt_pk_bf16_f32 v182, v0, v159
	v_cvt_pk_bf16_f32 v183, v161, v163
	v_cvt_pk_bf16_f32 v184, v165, v167
	v_cvt_pk_bf16_f32 v185, v169, v181
	v_add_f32_e32 v0, v46, v142
	v_add_f32_e32 v159, v47, v143
	v_add_f32_e32 v161, v48, v144
	v_add_f32_e32 v163, v49, v145
	v_add_f32_e32 v165, v42, v138
	v_add_f32_e32 v167, v43, v139
	v_add_f32_e32 v169, v44, v140
	v_add_f32_e32 v181, v45, v141
	v_mul_f32_e32 v0, 0xbfb8aa3b, v0
	v_mul_f32_e32 v159, 0xbfb8aa3b, v159
	v_mul_f32_e32 v161, 0xbfb8aa3b, v161
	v_mul_f32_e32 v163, 0xbfb8aa3b, v163
	v_mul_f32_e32 v165, 0xbfb8aa3b, v165
	v_mul_f32_e32 v167, 0xbfb8aa3b, v167
	v_mul_f32_e32 v169, 0xbfb8aa3b, v169
	v_mul_f32_e32 v181, 0xbfb8aa3b, v181
	v_exp_f32_e32 v0, v0
	v_exp_f32_e32 v159, v159
	v_exp_f32_e32 v161, v161
	v_exp_f32_e32 v163, v163
	v_exp_f32_e32 v165, v165
	v_exp_f32_e32 v167, v167
	v_exp_f32_e32 v169, v169
	v_exp_f32_e32 v181, v181
	v_add_f32_e32 v0, 1.0, v0
	v_add_f32_e32 v159, 1.0, v159
	v_add_f32_e32 v161, 1.0, v161
	v_add_f32_e32 v163, 1.0, v163
	v_add_f32_e32 v165, 1.0, v165
	v_add_f32_e32 v167, 1.0, v167
	v_add_f32_e32 v169, 1.0, v169
	v_add_f32_e32 v181, 1.0, v181
	v_rcp_f32_e32 v0, v0
	v_rcp_f32_e32 v159, v159
	v_rcp_f32_e32 v161, v161
	v_rcp_f32_e32 v163, v163
	v_rcp_f32_e32 v165, v165
	v_rcp_f32_e32 v167, v167
	v_rcp_f32_e32 v169, v169
	v_rcp_f32_e32 v181, v181
	global_store_dwordx4 v[174:175], v[182:185], off offset:256
	v_mad_i64_i32 v[174:175], s[0:1], v160, s2, v[170:171]
	s_nop 0
	v_cvt_pk_bf16_f32 v182, v0, v159
	v_cvt_pk_bf16_f32 v183, v161, v163
	v_cvt_pk_bf16_f32 v184, v165, v167
	v_cvt_pk_bf16_f32 v185, v169, v181
	v_add_f32_e32 v0, v38, v134
	v_add_f32_e32 v159, v39, v135
	v_add_f32_e32 v161, v40, v136
	v_add_f32_e32 v163, v41, v137
	v_add_f32_e32 v165, v34, v130
	v_add_f32_e32 v167, v35, v131
	v_add_f32_e32 v169, v36, v132
	v_add_f32_e32 v181, v37, v133
	v_mul_f32_e32 v0, 0xbfb8aa3b, v0
	v_mul_f32_e32 v159, 0xbfb8aa3b, v159
	v_mul_f32_e32 v161, 0xbfb8aa3b, v161
	v_mul_f32_e32 v163, 0xbfb8aa3b, v163
	v_mul_f32_e32 v165, 0xbfb8aa3b, v165
	v_mul_f32_e32 v167, 0xbfb8aa3b, v167
	v_mul_f32_e32 v169, 0xbfb8aa3b, v169
	v_mul_f32_e32 v181, 0xbfb8aa3b, v181
	v_exp_f32_e32 v0, v0
	v_exp_f32_e32 v159, v159
	v_exp_f32_e32 v161, v161
	v_exp_f32_e32 v163, v163
	v_exp_f32_e32 v165, v165
	v_exp_f32_e32 v167, v167
	v_exp_f32_e32 v169, v169
	v_exp_f32_e32 v181, v181
	v_add_f32_e32 v0, 1.0, v0
	v_add_f32_e32 v159, 1.0, v159
	v_add_f32_e32 v161, 1.0, v161
; __device__ __forceinline__ unsigned cvt_pk_bf16(float lo, float hi) { f32x2 v = {lo, hi}; bf16x2_t b = __builtin_convertvector(v, bf16x2_t); return __builtin_bit_cast(unsigned, b); }
; __device__ __forceinline__ float fast_exp2(float x) { return __builtin_amdgcn_exp2f(x); }
; __device__ __forceinline__ float fast_rcp(float x) { return __builtin_amdgcn_rcpf(x); }
;     __device__ __forceinline__ void operator()(ACC_T, const Unit& u, int wr, int wc, int fr, int fq) const {
;     ...
;             for (int ai = 0; ai < 2; ++ai)
; #pragma unroll
;                 for (int m = 0; m < 4; ++m) { bf16_t* rowp = Gt + (size_t)(row0 + ai * HALF + m * 16) * GW + col0;
; #pragma unroll
;                     for (int bj = 0; bj < 2; ++bj) { float r[8];
; #pragma unroll
;                         for (int n = 0; n < 2; ++n)
; #pragma unroll
;                             for (int e = 0; e < 4; ++e) { const float x = acc[ai][bj][m][n][e] + bv[bj][n][e]; r[n * 4 + e] = fast_rcp(1.f + fast_exp2(-x * LOG2E)); }
;                         u32x4 w; w.x = cvt_pk_bf16(r[0], r[1]); w.y = cvt_pk_bf16(r[2], r[3]); w.z = cvt_pk_bf16(r[4], r[5]); w.w = cvt_pk_bf16(r[6], r[7]);
;                         *(u32x4*)(rowp + bj * HALF) = w; } }
	v_add_f32_e32 v163, 1.0, v163
	v_add_f32_e32 v165, 1.0, v165
	v_add_f32_e32 v167, 1.0, v167
	v_add_f32_e32 v169, 1.0, v169
	v_add_f32_e32 v181, 1.0, v181
	v_rcp_f32_e32 v0, v0
	v_rcp_f32_e32 v159, v159
	v_rcp_f32_e32 v161, v161
	v_rcp_f32_e32 v163, v163
	v_rcp_f32_e32 v165, v165
	v_rcp_f32_e32 v167, v167
	v_rcp_f32_e32 v169, v169
	v_rcp_f32_e32 v181, v181
	v_lshl_add_u64 v[174:175], v[174:175], 0, v[172:173]
	global_store_dwordx4 v[174:175], v[182:185], off
	s_nop 1
	v_cvt_pk_bf16_f32 v182, v0, v159
	v_cvt_pk_bf16_f32 v183, v161, v163
	v_cvt_pk_bf16_f32 v184, v165, v167
	v_cvt_pk_bf16_f32 v185, v169, v181
	v_add_u32_e32 v0, 0xa0, v158
	global_store_dwordx4 v[174:175], v[182:185], off offset:256
	v_mad_i64_i32 v[174:175], s[0:1], v0, s2, v[170:171]
	v_add_f32_e32 v0, v30, v142
	v_add_f32_e32 v159, v31, v143
	v_mul_f32_e32 v0, 0xbfb8aa3b, v0
	v_mul_f32_e32 v159, 0xbfb8aa3b, v159
	v_exp_f32_e32 v0, v0
	v_exp_f32_e32 v159, v159
	v_add_f32_e32 v161, v32, v144
	v_add_f32_e32 v163, v33, v145
	v_add_f32_e32 v0, 1.0, v0
	v_add_f32_e32 v159, 1.0, v159
	v_rcp_f32_e32 v0, v0
	v_rcp_f32_e32 v159, v159
	v_add_f32_e32 v165, v26, v138
	v_add_f32_e32 v167, v27, v139
	v_add_f32_e32 v169, v28, v140
	v_add_f32_e32 v181, v29, v141
	v_mul_f32_e32 v161, 0xbfb8aa3b, v161
	v_mul_f32_e32 v163, 0xbfb8aa3b, v163
	v_mul_f32_e32 v165, 0xbfb8aa3b, v165
	v_mul_f32_e32 v167, 0xbfb8aa3b, v167
	v_mul_f32_e32 v169, 0xbfb8aa3b, v169
	v_mul_f32_e32 v181, 0xbfb8aa3b, v181
	v_cvt_pk_bf16_f32 v182, v0, v159
	v_add_f32_e32 v0, v22, v134
	v_add_f32_e32 v159, v23, v135
	v_exp_f32_e32 v161, v161
	v_exp_f32_e32 v163, v163
	v_exp_f32_e32 v165, v165
	v_exp_f32_e32 v167, v167
	v_exp_f32_e32 v169, v169
	v_exp_f32_e32 v181, v181
	v_mul_f32_e32 v0, 0xbfb8aa3b, v0
	v_mul_f32_e32 v159, 0xbfb8aa3b, v159
	v_exp_f32_e32 v0, v0
	v_exp_f32_e32 v159, v159
	v_add_f32_e32 v161, 1.0, v161
	v_add_f32_e32 v163, 1.0, v163
	v_add_f32_e32 v165, 1.0, v165
	v_add_f32_e32 v167, 1.0, v167
	v_add_f32_e32 v169, 1.0, v169
	v_add_f32_e32 v181, 1.0, v181
	v_add_f32_e32 v138, v10, v138
	v_rcp_f32_e32 v161, v161
	v_rcp_f32_e32 v163, v163
	v_rcp_f32_e32 v165, v165
	v_rcp_f32_e32 v167, v167
	v_rcp_f32_e32 v169, v169
	v_rcp_f32_e32 v181, v181
	v_add_f32_e32 v0, 1.0, v0
	v_add_f32_e32 v159, 1.0, v159
	v_mul_f32_e32 v138, 0xbfb8aa3b, v138
	v_rcp_f32_e32 v0, v0
	v_rcp_f32_e32 v159, v159
	v_exp_f32_e32 v138, v138
	v_lshl_add_u64 v[174:175], v[174:175], 0, v[172:173]
	v_cvt_pk_bf16_f32 v183, v161, v163
	v_cvt_pk_bf16_f32 v184, v165, v167
	v_cvt_pk_bf16_f32 v185, v169, v181
	global_store_dwordx4 v[174:175], v[182:185], off
	v_add_f32_e32 v138, 1.0, v138
	v_add_f32_e32 v161, v24, v136
	v_cvt_pk_bf16_f32 v182, v0, v159
	v_add_u32_e32 v0, 0xb0, v158
	v_mad_i64_i32 v[170:171], s[0:1], v0, s2, v[170:171]
	v_add_f32_e32 v0, v14, v142
	v_add_f32_e32 v142, v15, v143
	v_add_f32_e32 v143, v16, v144
	v_add_f32_e32 v144, v17, v145
	v_rcp_f32_e32 v145, v138
	v_add_f32_e32 v138, v11, v139
	v_mul_f32_e32 v138, 0xbfb8aa3b, v138
	v_exp_f32_e32 v138, v138
	v_add_f32_e32 v163, v25, v137
	v_mul_f32_e32 v161, 0xbfb8aa3b, v161
	v_mul_f32_e32 v163, 0xbfb8aa3b, v163
	v_exp_f32_e32 v161, v161
	v_exp_f32_e32 v163, v163
	v_add_f32_e32 v138, 1.0, v138
	v_rcp_f32_e32 v159, v138
	v_add_f32_e32 v138, v12, v140
	v_mul_f32_e32 v138, 0xbfb8aa3b, v138
	v_add_f32_e32 v161, 1.0, v161
	v_add_f32_e32 v163, 1.0, v163
	v_exp_f32_e32 v138, v138
	v_rcp_f32_e32 v161, v161
	v_rcp_f32_e32 v163, v163
	v_mul_f32_e32 v0, 0xbfb8aa3b, v0
	v_mul_f32_e32 v142, 0xbfb8aa3b, v142
	v_exp_f32_e32 v0, v0
	v_exp_f32_e32 v142, v142
	v_add_f32_e32 v138, 1.0, v138
	v_add_f32_e32 v165, v18, v130
	v_cvt_pk_bf16_f32 v183, v161, v163
	v_rcp_f32_e32 v161, v138
	v_add_f32_e32 v138, v13, v141
	v_add_f32_e32 v130, v2, v130
	v_mul_f32_e32 v138, 0xbfb8aa3b, v138
	v_mul_f32_e32 v130, 0xbfb8aa3b, v130
	v_add_f32_e32 v0, 1.0, v0
	v_add_f32_e32 v142, 1.0, v142
	v_exp_f32_e32 v138, v138
	v_exp_f32_e32 v130, v130
	v_rcp_f32_e32 v0, v0
	v_rcp_f32_e32 v142, v142
	v_mul_f32_e32 v143, 0xbfb8aa3b, v143
	v_mul_f32_e32 v144, 0xbfb8aa3b, v144
	v_exp_f32_e32 v143, v143
	v_exp_f32_e32 v144, v144
	v_add_f32_e32 v138, 1.0, v138
	v_add_f32_e32 v130, 1.0, v130
	v_rcp_f32_e32 v141, v138
	v_cvt_pk_bf16_f32 v138, v0, v142
	v_add_f32_e32 v0, v6, v134
	v_add_f32_e32 v134, v7, v135
	v_add_f32_e32 v135, v8, v136
	v_add_f32_e32 v136, v9, v137
	v_rcp_f32_e32 v137, v130
	v_add_f32_e32 v130, v3, v131
	v_add_f32_e32 v143, 1.0, v143
	v_add_f32_e32 v144, 1.0, v144
	v_mul_f32_e32 v130, 0xbfb8aa3b, v130
	v_rcp_f32_e32 v143, v143
	v_rcp_f32_e32 v144, v144
	v_exp_f32_e32 v130, v130
	v_lshl_add_u64 v[170:171], v[170:171], 0, v[172:173]
	v_cvt_pk_bf16_f32 v140, v145, v159
	v_cvt_pk_bf16_f32 v139, v143, v144
	v_cvt_pk_bf16_f32 v141, v161, v141
	v_add_f32_e32 v130, 1.0, v130
	global_store_dwordx4 v[170:171], v[138:141], off
	v_add_f32_e32 v167, v19, v131
	v_add_f32_e32 v169, v20, v132
	v_rcp_f32_e32 v138, v130
	v_add_f32_e32 v130, v4, v132
	v_mul_f32_e32 v130, 0xbfb8aa3b, v130
	v_exp_f32_e32 v130, v130
	v_add_f32_e32 v181, v21, v133
	v_mul_f32_e32 v165, 0xbfb8aa3b, v165
	v_mul_f32_e32 v167, 0xbfb8aa3b, v167
	v_add_f32_e32 v130, 1.0, v130
	v_rcp_f32_e32 v139, v130
	v_add_f32_e32 v130, v5, v133
	v_mul_f32_e32 v169, 0xbfb8aa3b, v169
	v_mul_f32_e32 v181, 0xbfb8aa3b, v181
	v_mul_f32_e32 v0, 0xbfb8aa3b, v0
	v_mul_f32_e32 v134, 0xbfb8aa3b, v134
	v_mul_f32_e32 v135, 0xbfb8aa3b, v135
	v_mul_f32_e32 v136, 0xbfb8aa3b, v136
	v_mul_f32_e32 v130, 0xbfb8aa3b, v130
	v_exp_f32_e32 v165, v165
	v_exp_f32_e32 v167, v167
	v_exp_f32_e32 v169, v169
	v_exp_f32_e32 v181, v181
	v_exp_f32_e32 v0, v0
	v_exp_f32_e32 v134, v134
	v_exp_f32_e32 v135, v135
	v_exp_f32_e32 v136, v136
	v_exp_f32_e32 v130, v130
	v_add_f32_e32 v165, 1.0, v165
	v_add_f32_e32 v167, 1.0, v167
	v_add_f32_e32 v169, 1.0, v169
	v_add_f32_e32 v181, 1.0, v181
	v_add_f32_e32 v0, 1.0, v0
	v_add_f32_e32 v134, 1.0, v134
	v_add_f32_e32 v135, 1.0, v135
	v_add_f32_e32 v136, 1.0, v136
	v_add_f32_e32 v130, 1.0, v130
	v_rcp_f32_e32 v165, v165
	v_rcp_f32_e32 v167, v167
	v_rcp_f32_e32 v169, v169
	v_rcp_f32_e32 v181, v181
	v_rcp_f32_e32 v0, v0
	v_rcp_f32_e32 v134, v134
	v_rcp_f32_e32 v135, v135
	v_rcp_f32_e32 v136, v136
	v_rcp_f32_e32 v133, v130
	v_cvt_pk_bf16_f32 v184, v165, v167
	v_cvt_pk_bf16_f32 v185, v169, v181
	v_cvt_pk_bf16_f32 v130, v0, v134
	v_cvt_pk_bf16_f32 v131, v135, v136
	v_cvt_pk_bf16_f32 v132, v137, v138
	v_cvt_pk_bf16_f32 v133, v139, v133
	global_store_dwordx4 v[174:175], v[182:185], off offset:256
	global_store_dwordx4 v[170:171], v[130:133], off offset:256
	s_mov_b64 s[0:1], 0

; #define PG8_WAIT_V(n) asm volatile("s_waitcnt vmcnt(" #n ")" ::: "memory")
; #define PG8_BAR __builtin_amdgcn_s_barrier()
; template <class Epi, bool ALIGN_EPI, bool ASLOT = false>
; __device__ __forceinline__ void gemm_phase(LAS unsigned char* lds, const Gemm g, const Sched& S, const Epi& E) {
;     ...
;         if (!has_next) break;
; #pragma unroll
;         for (int a = 0; a < 2; ++a)
; #pragma unroll
;             for (int b = 0; b < 2; ++b)
; #pragma unroll
;                 for (int m = 0; m < 4; ++m)
; #pragma unroll
;                     for (int n = 0; n < 2; ++n) acc[a][b][m][n] = (f32x4){0.f, 0.f, 0.f, 0.f};
;         cur = nxt; cA = nA; cB = nB; ++ui;
;         if constexpr (ALIGN_EPI) { if (wr == 1) PG8_BAR; }
;     }
;     PG8_WAIT_V(0);
;     if constexpr (!ALIGN_EPI) { if (wr == 0) PG8_BAR; }
;     PG8_BAR;
.LBB0_370:
	s_andn2_b64 vcc, exec, s[38:39]
	s_mov_b64 s[0:1], -1
	s_cbranch_vccnz .LBB0_296
	s_branch .LBB0_295
.LBB0_373:
	s_and_b64 vcc, exec, s[12:13]
	s_cbranch_vccz .Lna_inproj
	s_barrier

; __device__ __forceinline__ unsigned cvt_pk_bf16(float lo, float hi) { f32x2 v = {lo, hi}; bf16x2_t b = __builtin_convertvector(v, bf16x2_t); return __builtin_bit_cast(unsigned, b); }
; __device__ __forceinline__ float fast_exp2(float x) { return __builtin_amdgcn_exp2f(x); }
; __device__ __forceinline__ float fast_rcp(float x) { return __builtin_amdgcn_rcpf(x); }
;     __device__ __forceinline__ void operator()(ACC_T, const Unit& u, int wr, int wc, int fr, int fq) const {
;         const int row0 = wr * 64 + fr, col0 = u.pn * HALF + wc * 32 + 8 * fq; bf16_t* Hp = H + (size_t)u.pm * (SLOTB / 2);
; #pragma unroll
;         for (int ai = 0; ai < 2; ++ai)
; #pragma unroll
;             for (int m = 0; m < 4; ++m) { bf16_t* rowp = Hp + (size_t)(row0 + ai * HALF + m * 16) * DFF + col0; float r[8];
; #pragma unroll
;                 for (int n = 0; n < 2; ++n)
; #pragma unroll
;                     for (int e = 0; e < 4; ++e) { const float g = acc[ai][0][m][n][e], up = acc[ai][1][m][n][e]; r[n * 4 + e] = g * fast_rcp(1.f + fast_exp2(-g * LOG2E)) * up; }
;                 u32x4 w; w.x = cvt_pk_bf16(r[0], r[1]); w.y = cvt_pk_bf16(r[2], r[3]); w.z = cvt_pk_bf16(r[4], r[5]); w.w = cvt_pk_bf16(r[6], r[7]);
;                 *(u32x4*)rowp = w; }
.LBB0_856:
	v_mul_f32_e32 v157, 0xbfb8aa3b, v126
	v_exp_f32_e32 v157, v157
	v_mul_f32_e32 v161, 0xbfb8aa3b, v127
	v_exp_f32_e32 v161, v161
	v_lshl_or_b32 v156, s2, 7, v159
	v_add_f32_e32 v157, 1.0, v157
	v_rcp_f32_e32 v162, v157
	v_add_f32_e32 v157, 1.0, v161
	v_rcp_f32_e32 v163, v157
	v_mul_f32_e32 v161, 0xbfb8aa3b, v128
	v_exp_f32_e32 v161, v161
	s_mul_i32 s2, s3, 0x1c0000
	v_pk_mul_f32 v[126:127], v[126:127], v[162:163]
	v_mul_f32_e32 v162, 0xbfb8aa3b, v129
	v_exp_f32_e32 v162, v162
	v_pk_mul_f32 v[118:119], v[126:127], v[118:119]
	v_add_f32_e32 v126, 1.0, v161
	v_mul_f32_e32 v161, 0xbfb8aa3b, v122
	v_add_f32_e32 v127, 1.0, v162
	v_rcp_f32_e32 v126, v126
	v_rcp_f32_e32 v127, v127
	v_exp_f32_e32 v161, v161
	v_mul_f32_e32 v162, 0xbfb8aa3b, v123
	v_exp_f32_e32 v162, v162
	v_pk_mul_f32 v[126:127], v[128:129], v[126:127]
	v_add_f32_e32 v128, 1.0, v161
	v_mul_f32_e32 v161, 0xbfb8aa3b, v124
	v_add_f32_e32 v129, 1.0, v162
	v_exp_f32_e32 v161, v161
	v_mul_f32_e32 v162, 0xbfb8aa3b, v125
	v_exp_f32_e32 v163, v162
	v_rcp_f32_e32 v128, v128
	v_add_f32_e32 v161, 1.0, v161
	v_rcp_f32_e32 v129, v129
	v_rcp_f32_e32 v162, v161
	v_add_f32_e32 v161, 1.0, v163
	v_rcp_f32_e32 v163, v161
	v_pk_mul_f32 v[122:123], v[122:123], v[128:129]
	v_readlane_b32 s18, v251, 56
	v_pk_mul_f32 v[122:123], v[122:123], v[114:115]
	v_pk_mul_f32 v[114:115], v[124:125], v[162:163]
	s_mul_hi_i32 s9, s3, 0x1c0000
	v_pk_mul_f32 v[124:125], v[114:115], v[116:117]
	v_mul_f32_e32 v115, 0xbfb8aa3b, v110
	v_exp_f32_e32 v116, v115
	v_mul_f32_e32 v115, 0xbfb8aa3b, v111
	v_exp_f32_e32 v117, v115
	v_readlane_b32 s19, v251, 57
	s_add_u32 s2, s18, s2
	s_addc_u32 s3, s19, s9
	v_ashrrev_i32_e32 v157, 31, v156
	v_add_f32_e32 v116, 1.0, v116
	v_lshl_add_u64 v[156:157], v[156:157], 1, s[2:3]
	v_pk_mul_f32 v[120:121], v[126:127], v[120:121]
	v_cvt_pk_bf16_f32 v114, v118, v119
	v_rcp_f32_e32 v118, v116
	v_add_f32_e32 v116, 1.0, v117
	v_lshl_add_u64 v[126:127], v[156:157], 0, v[136:137]
	v_cvt_pk_bf16_f32 v115, v120, v121
	v_rcp_f32_e32 v119, v116
	v_cvt_pk_bf16_f32 v116, v122, v123
	v_cvt_pk_bf16_f32 v117, v124, v125
	global_store_dwordx4 v[126:127], v[114:117], off
	v_pk_mul_f32 v[110:111], v[110:111], v[118:119]
	v_readlane_b32 s22, v254, 52
	v_mul_f32_e32 v114, 0xbfb8aa3b, v112
	v_mul_f32_e32 v115, 0xbfb8aa3b, v113
	v_exp_f32_e32 v114, v114
	v_exp_f32_e32 v115, v115
	v_pk_mul_f32 v[102:103], v[110:111], v[102:103]
	s_andn2_b64 vcc, exec, s[40:41]
	v_add_f32_e32 v110, 1.0, v114
	v_add_f32_e32 v111, 1.0, v115
	v_mul_f32_e32 v114, 0xbfb8aa3b, v106
	v_mul_f32_e32 v115, 0xbfb8aa3b, v107
	v_rcp_f32_e32 v110, v110
	v_rcp_f32_e32 v111, v111
	v_exp_f32_e32 v114, v114
	v_exp_f32_e32 v115, v115
	s_mov_b64 s[18:19], -1
	v_pk_mul_f32 v[110:111], v[112:113], v[110:111]
	v_add_f32_e32 v112, 1.0, v114
	v_add_f32_e32 v113, 1.0, v115
	v_mul_f32_e32 v114, 0xbfb8aa3b, v108
	v_mul_f32_e32 v115, 0xbfb8aa3b, v109
	v_exp_f32_e32 v114, v114
	v_exp_f32_e32 v115, v115
	v_rcp_f32_e32 v112, v112
	v_rcp_f32_e32 v113, v113
	v_add_f32_e32 v114, 1.0, v114
	v_add_f32_e32 v115, 1.0, v115
	v_rcp_f32_e32 v114, v114
	v_rcp_f32_e32 v115, v115
	v_pk_mul_f32 v[106:107], v[106:107], v[112:113]
	v_pk_mul_f32 v[104:105], v[110:111], v[104:105]
	v_pk_mul_f32 v[106:107], v[106:107], v[98:99]
	v_pk_mul_f32 v[98:99], v[108:109], v[114:115]
	v_lshl_add_u64 v[110:111], v[156:157], 0, v[138:139]
	v_pk_mul_f32 v[108:109], v[98:99], v[100:101]
	v_mul_f32_e32 v99, 0xbfb8aa3b, v94
	v_exp_f32_e32 v100, v99
	v_mul_f32_e32 v99, 0xbfb8aa3b, v95
	v_exp_f32_e32 v101, v99
	v_cvt_pk_bf16_f32 v98, v102, v103
	v_add_f32_e32 v100, 1.0, v100
	v_rcp_f32_e32 v102, v100
	v_add_f32_e32 v100, 1.0, v101
	v_cvt_pk_bf16_f32 v99, v104, v105
	v_rcp_f32_e32 v103, v100
	v_cvt_pk_bf16_f32 v100, v106, v107
	v_cvt_pk_bf16_f32 v101, v108, v109
	global_store_dwordx4 v[110:111], v[98:101], off
	v_pk_mul_f32 v[94:95], v[94:95], v[102:103]
	v_readlane_b32 s23, v254, 53
	v_mul_f32_e32 v98, 0xbfb8aa3b, v96
	v_mul_f32_e32 v99, 0xbfb8aa3b, v97
	v_exp_f32_e32 v98, v98
	v_exp_f32_e32 v99, v99
	v_pk_mul_f32 v[86:87], v[94:95], v[86:87]
	v_add_f32_e32 v94, 1.0, v98
	v_add_f32_e32 v95, 1.0, v99
	v_mul_f32_e32 v98, 0xbfb8aa3b, v90
	v_mul_f32_e32 v99, 0xbfb8aa3b, v91
	v_rcp_f32_e32 v94, v94
	v_rcp_f32_e32 v95, v95
	v_exp_f32_e32 v98, v98
	v_exp_f32_e32 v99, v99
	v_pk_mul_f32 v[94:95], v[96:97], v[94:95]
	v_add_f32_e32 v96, 1.0, v98
	v_add_f32_e32 v97, 1.0, v99
	v_mul_f32_e32 v98, 0xbfb8aa3b, v92
	v_mul_f32_e32 v99, 0xbfb8aa3b, v93
	v_exp_f32_e32 v98, v98
	v_exp_f32_e32 v99, v99
	v_rcp_f32_e32 v96, v96
	v_rcp_f32_e32 v97, v97
	v_add_f32_e32 v98, 1.0, v98
	v_add_f32_e32 v99, 1.0, v99
	v_rcp_f32_e32 v98, v98
	v_rcp_f32_e32 v99, v99
	v_pk_mul_f32 v[90:91], v[90:91], v[96:97]
	v_pk_mul_f32 v[88:89], v[94:95], v[88:89]
	v_pk_mul_f32 v[90:91], v[90:91], v[82:83]
	v_pk_mul_f32 v[82:83], v[92:93], v[98:99]
	v_lshl_add_u64 v[94:95], v[156:157], 0, v[140:141]
	v_pk_mul_f32 v[92:93], v[82:83], v[84:85]
	v_mul_f32_e32 v83, 0xbfb8aa3b, v78
	v_exp_f32_e32 v84, v83
	v_mul_f32_e32 v83, 0xbfb8aa3b, v79
	v_exp_f32_e32 v85, v83
	v_cvt_pk_bf16_f32 v82, v86, v87
	v_add_f32_e32 v84, 1.0, v84
	v_rcp_f32_e32 v86, v84
	v_add_f32_e32 v84, 1.0, v85
	v_cvt_pk_bf16_f32 v83, v88, v89
	v_rcp_f32_e32 v87, v84
	v_cvt_pk_bf16_f32 v84, v90, v91
	v_cvt_pk_bf16_f32 v85, v92, v93
	global_store_dwordx4 v[94:95], v[82:85], off
	v_pk_mul_f32 v[78:79], v[78:79], v[86:87]
	s_nop 0
	v_mul_f32_e32 v82, 0xbfb8aa3b, v80
	v_mul_f32_e32 v83, 0xbfb8aa3b, v81
	v_exp_f32_e32 v82, v82
	v_exp_f32_e32 v83, v83
	v_pk_mul_f32 v[70:71], v[78:79], v[70:71]
	v_add_f32_e32 v78, 1.0, v82
	v_add_f32_e32 v79, 1.0, v83
	v_mul_f32_e32 v82, 0xbfb8aa3b, v74
; __device__ __forceinline__ unsigned cvt_pk_bf16(float lo, float hi) { f32x2 v = {lo, hi}; bf16x2_t b = __builtin_convertvector(v, bf16x2_t); return __builtin_bit_cast(unsigned, b); }
; __device__ __forceinline__ float fast_exp2(float x) { return __builtin_amdgcn_exp2f(x); }
; __device__ __forceinline__ float fast_rcp(float x) { return __builtin_amdgcn_rcpf(x); }
; #define PG8_WAIT_V(n) asm volatile("s_waitcnt vmcnt(" #n ")" ::: "memory")
; #define PG8_BAR __builtin_amdgcn_s_barrier()
;     __device__ __forceinline__ void operator()(ACC_T, const Unit& u, int wr, int wc, int fr, int fq) const {
;     ...
;             for (int m = 0; m < 4; ++m) { bf16_t* rowp = Hp + (size_t)(row0 + ai * HALF + m * 16) * DFF + col0; float r[8];
; #pragma unroll
;                 for (int n = 0; n < 2; ++n)
; #pragma unroll
;                     for (int e = 0; e < 4; ++e) { const float g = acc[ai][0][m][n][e], up = acc[ai][1][m][n][e]; r[n * 4 + e] = g * fast_rcp(1.f + fast_exp2(-g * LOG2E)) * up; }
;                 u32x4 w; w.x = cvt_pk_bf16(r[0], r[1]); w.y = cvt_pk_bf16(r[2], r[3]); w.z = cvt_pk_bf16(r[4], r[5]); w.w = cvt_pk_bf16(r[6], r[7]);
;                 *(u32x4*)rowp = w; }
; template <class Epi, bool ALIGN_EPI, bool ASLOT = false>
; __device__ __forceinline__ void gemm_phase(LAS unsigned char* lds, const Gemm g, const Sched& S, const Epi& E) {
;     ...
;         if (!has_next) break;
; #pragma unroll
;         for (int a = 0; a < 2; ++a)
; #pragma unroll
;             for (int b = 0; b < 2; ++b)
; #pragma unroll
;                 for (int m = 0; m < 4; ++m)
; #pragma unroll
;                     for (int n = 0; n < 2; ++n) acc[a][b][m][n] = (f32x4){0.f, 0.f, 0.f, 0.f};
;         cur = nxt; cA = nA; cB = nB; ++ui;
;         if constexpr (ALIGN_EPI) { if (wr == 1) PG8_BAR; }
;     }
;     PG8_WAIT_V(0);
;     if constexpr (!ALIGN_EPI) { if (wr == 0) PG8_BAR; }
	v_mul_f32_e32 v83, 0xbfb8aa3b, v75
	v_rcp_f32_e32 v78, v78
	v_rcp_f32_e32 v79, v79
	v_exp_f32_e32 v82, v82
	v_exp_f32_e32 v83, v83
	v_pk_mul_f32 v[78:79], v[80:81], v[78:79]
	v_add_f32_e32 v80, 1.0, v82
	v_add_f32_e32 v81, 1.0, v83
	v_mul_f32_e32 v82, 0xbfb8aa3b, v76
	v_mul_f32_e32 v83, 0xbfb8aa3b, v77
	v_exp_f32_e32 v82, v82
	v_exp_f32_e32 v83, v83
	v_rcp_f32_e32 v80, v80
	v_rcp_f32_e32 v81, v81
	v_add_f32_e32 v82, 1.0, v82
	v_add_f32_e32 v83, 1.0, v83
	v_rcp_f32_e32 v82, v82
	v_rcp_f32_e32 v83, v83
	v_pk_mul_f32 v[74:75], v[74:75], v[80:81]
	v_pk_mul_f32 v[72:73], v[78:79], v[72:73]
	v_pk_mul_f32 v[74:75], v[74:75], v[66:67]
	v_pk_mul_f32 v[66:67], v[76:77], v[82:83]
	v_lshl_add_u64 v[78:79], v[156:157], 0, v[142:143]
	v_pk_mul_f32 v[76:77], v[66:67], v[68:69]
	v_mul_f32_e32 v67, 0xbfb8aa3b, v62
	v_exp_f32_e32 v68, v67
	v_mul_f32_e32 v67, 0xbfb8aa3b, v63
	v_exp_f32_e32 v69, v67
	v_cvt_pk_bf16_f32 v66, v70, v71
	v_add_f32_e32 v68, 1.0, v68
	v_rcp_f32_e32 v70, v68
	v_add_f32_e32 v68, 1.0, v69
	v_cvt_pk_bf16_f32 v67, v72, v73
	v_rcp_f32_e32 v71, v68
	v_cvt_pk_bf16_f32 v68, v74, v75
	v_cvt_pk_bf16_f32 v69, v76, v77
	global_store_dwordx4 v[78:79], v[66:69], off
	v_pk_mul_f32 v[62:63], v[62:63], v[70:71]
	s_nop 0
	v_mul_f32_e32 v66, 0xbfb8aa3b, v64
	v_mul_f32_e32 v67, 0xbfb8aa3b, v65
	v_exp_f32_e32 v66, v66
	v_exp_f32_e32 v67, v67
	v_pk_mul_f32 v[54:55], v[62:63], v[54:55]
	v_add_f32_e32 v62, 1.0, v66
	v_add_f32_e32 v63, 1.0, v67
	v_mul_f32_e32 v66, 0xbfb8aa3b, v58
	v_mul_f32_e32 v67, 0xbfb8aa3b, v59
	v_rcp_f32_e32 v62, v62
	v_rcp_f32_e32 v63, v63
	v_exp_f32_e32 v66, v66
	v_exp_f32_e32 v67, v67
	v_pk_mul_f32 v[62:63], v[64:65], v[62:63]
	v_add_f32_e32 v64, 1.0, v66
	v_add_f32_e32 v65, 1.0, v67
	v_mul_f32_e32 v66, 0xbfb8aa3b, v60
	v_mul_f32_e32 v67, 0xbfb8aa3b, v61
	v_exp_f32_e32 v66, v66
	v_exp_f32_e32 v67, v67
	v_rcp_f32_e32 v64, v64
	v_rcp_f32_e32 v65, v65
	v_add_f32_e32 v66, 1.0, v66
	v_add_f32_e32 v67, 1.0, v67
	v_rcp_f32_e32 v66, v66
	v_rcp_f32_e32 v67, v67
	v_pk_mul_f32 v[58:59], v[58:59], v[64:65]
	v_pk_mul_f32 v[56:57], v[62:63], v[56:57]
	v_pk_mul_f32 v[58:59], v[58:59], v[50:51]
	v_pk_mul_f32 v[50:51], v[60:61], v[66:67]
	v_lshl_add_u64 v[62:63], v[156:157], 0, v[144:145]
	v_pk_mul_f32 v[60:61], v[50:51], v[52:53]
	v_mul_f32_e32 v51, 0xbfb8aa3b, v46
	v_exp_f32_e32 v52, v51
	v_mul_f32_e32 v51, 0xbfb8aa3b, v47
	v_exp_f32_e32 v53, v51
	v_cvt_pk_bf16_f32 v50, v54, v55
	v_add_f32_e32 v52, 1.0, v52
	v_rcp_f32_e32 v54, v52
	v_add_f32_e32 v52, 1.0, v53
	v_cvt_pk_bf16_f32 v51, v56, v57
	v_rcp_f32_e32 v55, v52
	v_cvt_pk_bf16_f32 v52, v58, v59
	v_cvt_pk_bf16_f32 v53, v60, v61
	global_store_dwordx4 v[62:63], v[50:53], off
	v_pk_mul_f32 v[46:47], v[46:47], v[54:55]
	s_nop 0
	v_mul_f32_e32 v50, 0xbfb8aa3b, v48
	v_mul_f32_e32 v51, 0xbfb8aa3b, v49
	v_exp_f32_e32 v50, v50
	v_exp_f32_e32 v51, v51
	v_pk_mul_f32 v[38:39], v[46:47], v[38:39]
	v_add_f32_e32 v46, 1.0, v50
	v_add_f32_e32 v47, 1.0, v51
	v_mul_f32_e32 v50, 0xbfb8aa3b, v42
	v_mul_f32_e32 v51, 0xbfb8aa3b, v43
	v_rcp_f32_e32 v46, v46
	v_rcp_f32_e32 v47, v47
	v_exp_f32_e32 v50, v50
	v_exp_f32_e32 v51, v51
	v_pk_mul_f32 v[46:47], v[48:49], v[46:47]
	v_add_f32_e32 v48, 1.0, v50
	v_add_f32_e32 v49, 1.0, v51
	v_mul_f32_e32 v50, 0xbfb8aa3b, v44
	v_mul_f32_e32 v51, 0xbfb8aa3b, v45
	v_exp_f32_e32 v50, v50
	v_exp_f32_e32 v51, v51
	v_rcp_f32_e32 v48, v48
	v_rcp_f32_e32 v49, v49
	v_add_f32_e32 v50, 1.0, v50
	v_add_f32_e32 v51, 1.0, v51
	v_rcp_f32_e32 v50, v50
	v_rcp_f32_e32 v51, v51
	v_pk_mul_f32 v[42:43], v[42:43], v[48:49]
	v_pk_mul_f32 v[40:41], v[46:47], v[40:41]
	v_pk_mul_f32 v[42:43], v[42:43], v[34:35]
	v_pk_mul_f32 v[34:35], v[44:45], v[50:51]
	v_lshl_add_u64 v[46:47], v[156:157], 0, v[146:147]
	v_pk_mul_f32 v[44:45], v[34:35], v[36:37]
	v_mul_f32_e32 v35, 0xbfb8aa3b, v30
	v_exp_f32_e32 v36, v35
	v_mul_f32_e32 v35, 0xbfb8aa3b, v31
	v_exp_f32_e32 v37, v35
	v_cvt_pk_bf16_f32 v34, v38, v39
	v_add_f32_e32 v36, 1.0, v36
	v_rcp_f32_e32 v38, v36
	v_add_f32_e32 v36, 1.0, v37
	v_cvt_pk_bf16_f32 v35, v40, v41
	v_rcp_f32_e32 v39, v36
	v_cvt_pk_bf16_f32 v36, v42, v43
	v_cvt_pk_bf16_f32 v37, v44, v45
	global_store_dwordx4 v[46:47], v[34:37], off
	v_pk_mul_f32 v[30:31], v[30:31], v[38:39]
	s_nop 0
	v_mul_f32_e32 v34, 0xbfb8aa3b, v32
	v_mul_f32_e32 v35, 0xbfb8aa3b, v33
	v_exp_f32_e32 v34, v34
	v_exp_f32_e32 v35, v35
	v_pk_mul_f32 v[22:23], v[30:31], v[22:23]
	v_add_f32_e32 v30, 1.0, v34
	v_add_f32_e32 v31, 1.0, v35
	v_mul_f32_e32 v34, 0xbfb8aa3b, v26
	v_mul_f32_e32 v35, 0xbfb8aa3b, v27
	v_rcp_f32_e32 v30, v30
	v_rcp_f32_e32 v31, v31
	v_exp_f32_e32 v34, v34
	v_exp_f32_e32 v35, v35
	v_pk_mul_f32 v[30:31], v[32:33], v[30:31]
	v_add_f32_e32 v32, 1.0, v34
	v_add_f32_e32 v33, 1.0, v35
	v_mul_f32_e32 v34, 0xbfb8aa3b, v28
	v_mul_f32_e32 v35, 0xbfb8aa3b, v29
	v_exp_f32_e32 v34, v34
	v_exp_f32_e32 v35, v35
	v_rcp_f32_e32 v32, v32
	v_rcp_f32_e32 v33, v33
	v_add_f32_e32 v34, 1.0, v34
	v_add_f32_e32 v35, 1.0, v35
	v_rcp_f32_e32 v34, v34
	v_rcp_f32_e32 v35, v35
	v_pk_mul_f32 v[26:27], v[26:27], v[32:33]
	v_pk_mul_f32 v[24:25], v[30:31], v[24:25]
	v_pk_mul_f32 v[26:27], v[26:27], v[18:19]
	v_pk_mul_f32 v[18:19], v[28:29], v[34:35]
	v_lshl_add_u64 v[30:31], v[156:157], 0, v[148:149]
	v_pk_mul_f32 v[28:29], v[18:19], v[20:21]
	v_mul_f32_e32 v19, 0xbfb8aa3b, v14
	v_exp_f32_e32 v20, v19
	v_mul_f32_e32 v19, 0xbfb8aa3b, v15
	v_exp_f32_e32 v21, v19
	v_cvt_pk_bf16_f32 v18, v22, v23
	v_add_f32_e32 v20, 1.0, v20
	v_rcp_f32_e32 v22, v20
	v_add_f32_e32 v20, 1.0, v21
	v_cvt_pk_bf16_f32 v19, v24, v25
	v_rcp_f32_e32 v23, v20
	v_cvt_pk_bf16_f32 v20, v26, v27
	v_cvt_pk_bf16_f32 v21, v28, v29
	global_store_dwordx4 v[30:31], v[18:21], off
	v_pk_mul_f32 v[14:15], v[14:15], v[22:23]
	s_nop 0
	v_mul_f32_e32 v18, 0xbfb8aa3b, v16
	v_mul_f32_e32 v19, 0xbfb8aa3b, v17
	v_exp_f32_e32 v18, v18
	v_exp_f32_e32 v19, v19
	v_pk_mul_f32 v[6:7], v[14:15], v[6:7]
	v_add_f32_e32 v14, 1.0, v18
	v_add_f32_e32 v15, 1.0, v19
	v_mul_f32_e32 v18, 0xbfb8aa3b, v10
	v_mul_f32_e32 v19, 0xbfb8aa3b, v11
	v_rcp_f32_e32 v14, v14
	v_rcp_f32_e32 v15, v15
	v_exp_f32_e32 v18, v18
	v_exp_f32_e32 v19, v19
	v_pk_mul_f32 v[14:15], v[16:17], v[14:15]
	v_add_f32_e32 v16, 1.0, v18
	v_add_f32_e32 v17, 1.0, v19
	v_mul_f32_e32 v18, 0xbfb8aa3b, v12
	v_mul_f32_e32 v19, 0xbfb8aa3b, v13
	v_exp_f32_e32 v18, v18
	v_exp_f32_e32 v19, v19
	v_rcp_f32_e32 v16, v16
	v_rcp_f32_e32 v17, v17
	v_add_f32_e32 v18, 1.0, v18
	v_add_f32_e32 v19, 1.0, v19
	v_rcp_f32_e32 v18, v18
	v_rcp_f32_e32 v19, v19
	v_pk_mul_f32 v[10:11], v[10:11], v[16:17]
	v_pk_mul_f32 v[8:9], v[14:15], v[8:9]
	v_pk_mul_f32 v[10:11], v[10:11], v[2:3]
	v_pk_mul_f32 v[2:3], v[12:13], v[18:19]
	v_lshl_add_u64 v[14:15], v[156:157], 0, v[150:151]
	v_pk_mul_f32 v[12:13], v[2:3], v[4:5]
	v_cvt_pk_bf16_f32 v2, v6, v7
	v_cvt_pk_bf16_f32 v3, v8, v9
	v_cvt_pk_bf16_f32 v4, v10, v11
	v_cvt_pk_bf16_f32 v5, v12, v13
	global_store_dwordx4 v[14:15], v[2:5], off
	s_cbranch_vccnz .LBB0_849
	s_branch .LBB0_848
.LBB0_859:
	s_and_b64 vcc, exec, s[6:7]
	s_cbranch_vccz .Lna_ffn2
	s_barrier
